# lane-linear fragment layout for NSA selected/window K,V (coalesced fragment loads); window units LDS-staged; chunk-state units via LDS; compress MLP pipelined
# speedup vs baseline: 1.0897x; 1.0897x over previous
.LBB0_149:
	s_mov_b64 s[56:57], 64
	s_mov_b64 s[6:7], 0
	s_andn2_b64 vcc, exec, s[0:1]
	s_mov_b64 s[2:3], s[30:31]
	s_mov_b64 s[0:1], 0
	v_mov_b64_e32 v[166:167], v[152:153]
	v_mov_b64_e32 v[168:169], v[152:153]
	s_cbranch_vccnz .LBB0_151
	s_mov_b64 s[56:57], 0
	s_mov_b64 s[2:3], -1
	v_and_b32_e32 v170, 15, v208
	v_bfe_u32 v171, v208, 4, 2
	v_mul_u32_u24_e32 v172, 0xf0, v171
	v_mul_u32_u24_e32 v173, 48, v170
	v_sub_u32_e32 v172, v172, v173
	v_ashrrev_i32_e32 v173, 31, v172
	v_lshl_add_u64 v[168:169], s[18:19], 0, v[172:173]
	v_lshrrev_b32_e32 v170, 2, v170
	v_and_b32_e32 v171, 1, v171
	v_mul_u32_u24_e32 v172, 0xf0, v170
	v_mul_u32_u24_e32 v173, 0x180, v171
	v_sub_u32_e32 v172, v172, v173
	v_ashrrev_i32_e32 v173, 31, v172
	v_lshl_add_u64 v[166:167], s[20:21], 0, v[172:173]
	s_mov_b64 s[0:1], -1
.LBB0_151:
	s_andn2_b64 vcc, exec, s[6:7]
	s_cbranch_vccnz .LBB0_153
	s_mov_b64 s[56:57], 0
	s_mov_b64 s[2:3], -1
	v_and_b32_e32 v170, 15, v208
	v_bfe_u32 v171, v208, 4, 2
	v_mul_u32_u24_e32 v172, 0xf0, v171
	v_mul_u32_u24_e32 v173, 48, v170
	v_sub_u32_e32 v172, v172, v173
	v_ashrrev_i32_e32 v173, 31, v172
	v_lshl_add_u64 v[168:169], s[22:23], 0, v[172:173]
	v_lshrrev_b32_e32 v170, 2, v170
	v_and_b32_e32 v171, 1, v171
	v_mul_u32_u24_e32 v172, 0xf0, v170
	v_mul_u32_u24_e32 v173, 0x180, v171
	v_sub_u32_e32 v172, v172, v173
	v_ashrrev_i32_e32 v173, 31, v172
	v_lshl_add_u64 v[166:167], s[24:25], 0, v[172:173]
	s_mov_b64 s[0:1], -1

.LBB0_168:
	s_andn2_b64 vcc, exec, s[0:1]
	s_cbranch_vccnz .LBB0_170
	s_ashr_i32 s0, s39, 5
	s_ashr_i32 s1, s0, 31
	s_lshl_b64 s[0:1], s[0:1], 12
	v_lshl_add_u64 v[144:145], v[166:167], 0, s[0:1]
	v_lshlrev_b32_e32 v64, 1, v156
	v_lshl_add_u64 v[144:145], v[144:145], 0, v[64:65]
	v_bfe_u32 v64, v122, 16, 1
	v_lshl_add_u64 v[144:145], v[144:145], 0, s[52:53]
	v_add3_u32 v146, v122, v64, s97
	v_lshlrev_b32_e32 v64, 1, v158
	v_lshl_add_u64 v[144:145], v[144:145], 0, v[64:65]
	v_bfe_u32 v64, v123, 16, 1
	v_add3_u32 v64, v123, v64, s97
	flat_store_short_d16_hi v[144:145], v64 offset:16
	v_bfe_u32 v64, v124, 16, 1
	v_add3_u32 v64, v124, v64, s97
	flat_store_short_d16_hi v[144:145], v64 offset:32
	v_bfe_u32 v64, v125, 16, 1
	v_add3_u32 v64, v125, v64, s97
	flat_store_short_d16_hi v[144:145], v64 offset:48
	v_bfe_u32 v64, v114, 16, 1
	v_add3_u32 v64, v114, v64, s97
	flat_store_short_d16_hi v[144:145], v64 offset:64
	v_bfe_u32 v64, v115, 16, 1
	v_add3_u32 v64, v115, v64, s97
	flat_store_short_d16_hi v[144:145], v64 offset:80
	v_bfe_u32 v64, v116, 16, 1
	v_add3_u32 v64, v116, v64, s97
	flat_store_short_d16_hi v[144:145], v64 offset:96
	v_bfe_u32 v64, v117, 16, 1
	v_add3_u32 v64, v117, v64, s97
	flat_store_short_d16_hi v[144:145], v146
	flat_store_short_d16_hi v[144:145], v64 offset:112

.LBB0_179:
	s_andn2_b64 vcc, exec, s[0:1]
	s_cbranch_vccnz .LBB0_181
	s_ashr_i32 s0, s39, 5
	s_ashr_i32 s1, s0, 31
	s_lshl_b64 s[0:1], s[0:1], 12
	v_lshl_add_u64 v[144:145], v[166:167], 0, s[0:1]
	v_lshlrev_b32_e32 v64, 1, v156
	v_lshl_add_u64 v[144:145], v[144:145], 0, v[64:65]
	v_bfe_u32 v64, v106, 16, 1
	v_lshl_add_u64 v[144:145], v[144:145], 0, s[52:53]
	v_add3_u32 v146, v106, v64, s97
	v_lshlrev_b32_e32 v64, 1, v158
	v_lshl_add_u64 v[144:145], v[144:145], 0, v[64:65]
	v_bfe_u32 v64, v107, 16, 1
	v_add3_u32 v64, v107, v64, s97
	flat_store_short_d16_hi v[144:145], v64 offset:24
	v_bfe_u32 v64, v108, 16, 1
	v_add3_u32 v64, v108, v64, s97
	flat_store_short_d16_hi v[144:145], v64 offset:40
	v_bfe_u32 v64, v109, 16, 1
	v_add3_u32 v64, v109, v64, s97
	flat_store_short_d16_hi v[144:145], v64 offset:56
	v_bfe_u32 v64, v98, 16, 1
	v_add3_u32 v64, v98, v64, s97
	flat_store_short_d16_hi v[144:145], v64 offset:72
	v_bfe_u32 v64, v99, 16, 1
	v_add3_u32 v64, v99, v64, s97
	flat_store_short_d16_hi v[144:145], v64 offset:88
	v_bfe_u32 v64, v100, 16, 1
	v_add3_u32 v64, v100, v64, s97
	flat_store_short_d16_hi v[144:145], v64 offset:104
	v_bfe_u32 v64, v101, 16, 1
	v_add3_u32 v64, v101, v64, s97
	flat_store_short_d16_hi v[144:145], v146 offset:8
	flat_store_short_d16_hi v[144:145], v64 offset:120

.LBB0_190:
	s_andn2_b64 vcc, exec, s[0:1]
	s_cbranch_vccnz .LBB0_192
	v_ashrrev_i32_e32 v144, 5, v64
	v_ashrrev_i32_e32 v145, 31, v144
	v_lshlrev_b64 v[144:145], 12, v[144:145]
	v_lshl_add_u64 v[144:145], v[166:167], 0, v[144:145]
	v_lshlrev_b32_e32 v64, 1, v156
	v_lshl_add_u64 v[144:145], v[144:145], 0, v[64:65]
	v_bfe_u32 v64, v90, 16, 1
	v_lshl_add_u64 v[144:145], v[144:145], 0, s[52:53]
	v_add3_u32 v146, v90, v64, s97
	v_lshlrev_b32_e32 v64, 1, v158
	v_lshl_add_u64 v[144:145], v[144:145], 0, v[64:65]
	v_bfe_u32 v64, v91, 16, 1
	v_add3_u32 v64, v91, v64, s97
	flat_store_short_d16_hi v[144:145], v64 offset:16
	v_bfe_u32 v64, v92, 16, 1
	v_add3_u32 v64, v92, v64, s97
	flat_store_short_d16_hi v[144:145], v64 offset:32
	v_bfe_u32 v64, v93, 16, 1
	v_add3_u32 v64, v93, v64, s97
	flat_store_short_d16_hi v[144:145], v64 offset:48
	v_bfe_u32 v64, v82, 16, 1
	v_add3_u32 v64, v82, v64, s97
	flat_store_short_d16_hi v[144:145], v64 offset:64
	v_bfe_u32 v64, v83, 16, 1
	v_add3_u32 v64, v83, v64, s97
	flat_store_short_d16_hi v[144:145], v64 offset:80
	v_bfe_u32 v64, v84, 16, 1
	v_add3_u32 v64, v84, v64, s97
	flat_store_short_d16_hi v[144:145], v64 offset:96
	v_bfe_u32 v64, v85, 16, 1
	v_add3_u32 v64, v85, v64, s97
	flat_store_short_d16_hi v[144:145], v146
	flat_store_short_d16_hi v[144:145], v64 offset:112

.LBB0_201:
	s_andn2_b64 vcc, exec, s[0:1]
	s_cbranch_vccnz .LBB0_203
	v_ashrrev_i32_e32 v144, 5, v64
	v_ashrrev_i32_e32 v145, 31, v144
	v_lshlrev_b64 v[144:145], 12, v[144:145]
	v_lshl_add_u64 v[144:145], v[166:167], 0, v[144:145]
	v_lshlrev_b32_e32 v64, 1, v156
	v_lshl_add_u64 v[144:145], v[144:145], 0, v[64:65]
	v_bfe_u32 v64, v74, 16, 1
	v_lshl_add_u64 v[144:145], v[144:145], 0, s[52:53]
	v_add3_u32 v146, v74, v64, s97
	v_lshlrev_b32_e32 v64, 1, v158
	v_lshl_add_u64 v[144:145], v[144:145], 0, v[64:65]
	v_bfe_u32 v64, v75, 16, 1
	v_add3_u32 v64, v75, v64, s97
	flat_store_short_d16_hi v[144:145], v64 offset:24
	v_bfe_u32 v64, v76, 16, 1
	v_add3_u32 v64, v76, v64, s97
	flat_store_short_d16_hi v[144:145], v64 offset:40
	v_bfe_u32 v64, v77, 16, 1
	v_add3_u32 v64, v77, v64, s97
	flat_store_short_d16_hi v[144:145], v64 offset:56
	v_bfe_u32 v64, v66, 16, 1
	v_add3_u32 v64, v66, v64, s97
	flat_store_short_d16_hi v[144:145], v64 offset:72
	v_bfe_u32 v64, v67, 16, 1
	v_add3_u32 v64, v67, v64, s97
	flat_store_short_d16_hi v[144:145], v64 offset:88
	v_bfe_u32 v64, v68, 16, 1
	v_add3_u32 v64, v68, v64, s97
	flat_store_short_d16_hi v[144:145], v64 offset:104
	v_bfe_u32 v64, v69, 16, 1
	v_add3_u32 v64, v69, v64, s97
	flat_store_short_d16_hi v[144:145], v146 offset:8
	flat_store_short_d16_hi v[144:145], v64 offset:120

.LBB0_212:
	s_andn2_b64 vcc, exec, s[0:1]
	s_cbranch_vccnz .LBB0_214
	v_ashrrev_i32_e32 v144, 5, v64
	v_ashrrev_i32_e32 v145, 31, v144
	v_lshlrev_b64 v[144:145], 12, v[144:145]
	v_lshl_add_u64 v[144:145], v[166:167], 0, v[144:145]
	v_lshlrev_b32_e32 v64, 1, v156
	v_lshl_add_u64 v[144:145], v[144:145], 0, v[64:65]
	v_bfe_u32 v64, v56, 16, 1
	v_lshl_add_u64 v[144:145], v[144:145], 0, s[52:53]
	v_add3_u32 v146, v56, v64, s97
	v_lshlrev_b32_e32 v64, 1, v158
	v_lshl_add_u64 v[144:145], v[144:145], 0, v[64:65]
	v_bfe_u32 v64, v57, 16, 1
	v_add3_u32 v64, v57, v64, s97
	flat_store_short_d16_hi v[144:145], v64 offset:16
	v_bfe_u32 v64, v58, 16, 1
	v_add3_u32 v64, v58, v64, s97
	flat_store_short_d16_hi v[144:145], v64 offset:32
	v_bfe_u32 v64, v59, 16, 1
	v_add3_u32 v64, v59, v64, s97
	flat_store_short_d16_hi v[144:145], v64 offset:48
	v_bfe_u32 v64, v48, 16, 1
	v_add3_u32 v64, v48, v64, s97
	flat_store_short_d16_hi v[144:145], v64 offset:64
	v_bfe_u32 v64, v49, 16, 1
	v_add3_u32 v64, v49, v64, s97
	flat_store_short_d16_hi v[144:145], v64 offset:80
	v_bfe_u32 v64, v50, 16, 1
	v_add3_u32 v64, v50, v64, s97
	flat_store_short_d16_hi v[144:145], v64 offset:96
	v_bfe_u32 v64, v51, 16, 1
	v_add3_u32 v64, v51, v64, s97
	flat_store_short_d16_hi v[144:145], v146
	flat_store_short_d16_hi v[144:145], v64 offset:112

.LBB0_223:
	s_andn2_b64 vcc, exec, s[0:1]
	s_cbranch_vccnz .LBB0_225
	v_ashrrev_i32_e32 v144, 5, v64
	v_ashrrev_i32_e32 v145, 31, v144
	v_lshlrev_b64 v[144:145], 12, v[144:145]
	v_lshl_add_u64 v[144:145], v[166:167], 0, v[144:145]
	v_lshlrev_b32_e32 v64, 1, v156
	v_lshl_add_u64 v[144:145], v[144:145], 0, v[64:65]
	v_bfe_u32 v64, v40, 16, 1
	v_lshl_add_u64 v[144:145], v[144:145], 0, s[52:53]
	v_add3_u32 v146, v40, v64, s97
	v_lshlrev_b32_e32 v64, 1, v158
	v_lshl_add_u64 v[144:145], v[144:145], 0, v[64:65]
	v_bfe_u32 v64, v41, 16, 1
	v_add3_u32 v64, v41, v64, s97
	flat_store_short_d16_hi v[144:145], v64 offset:24
	v_bfe_u32 v64, v42, 16, 1
	v_add3_u32 v64, v42, v64, s97
	flat_store_short_d16_hi v[144:145], v64 offset:40
	v_bfe_u32 v64, v43, 16, 1
	v_add3_u32 v64, v43, v64, s97
	flat_store_short_d16_hi v[144:145], v64 offset:56
	v_bfe_u32 v64, v32, 16, 1
	v_add3_u32 v64, v32, v64, s97
	flat_store_short_d16_hi v[144:145], v64 offset:72
	v_bfe_u32 v64, v33, 16, 1
	v_add3_u32 v64, v33, v64, s97
	flat_store_short_d16_hi v[144:145], v64 offset:88
	v_bfe_u32 v64, v34, 16, 1
	v_add3_u32 v64, v34, v64, s97
	flat_store_short_d16_hi v[144:145], v64 offset:104
	v_bfe_u32 v64, v35, 16, 1
	v_add3_u32 v64, v35, v64, s97
	flat_store_short_d16_hi v[144:145], v146 offset:8
	flat_store_short_d16_hi v[144:145], v64 offset:120

.LBB0_234:
	s_andn2_b64 vcc, exec, s[0:1]
	s_cbranch_vccnz .LBB0_236
	v_ashrrev_i32_e32 v144, 5, v64
	v_ashrrev_i32_e32 v145, 31, v144
	v_lshlrev_b64 v[144:145], 12, v[144:145]
	v_lshl_add_u64 v[144:145], v[166:167], 0, v[144:145]
	v_lshlrev_b32_e32 v64, 1, v156
	v_lshl_add_u64 v[144:145], v[144:145], 0, v[64:65]
	v_bfe_u32 v64, v24, 16, 1
	v_lshl_add_u64 v[144:145], v[144:145], 0, s[52:53]
	v_add3_u32 v146, v24, v64, s97
	v_lshlrev_b32_e32 v64, 1, v158
	v_lshl_add_u64 v[144:145], v[144:145], 0, v[64:65]
	v_bfe_u32 v64, v25, 16, 1
	v_add3_u32 v64, v25, v64, s97
	flat_store_short_d16_hi v[144:145], v64 offset:16
	v_bfe_u32 v64, v26, 16, 1
	v_add3_u32 v64, v26, v64, s97
	flat_store_short_d16_hi v[144:145], v64 offset:32
	v_bfe_u32 v64, v27, 16, 1
	v_add3_u32 v64, v27, v64, s97
	flat_store_short_d16_hi v[144:145], v64 offset:48
	v_bfe_u32 v64, v16, 16, 1
	v_add3_u32 v64, v16, v64, s97
	flat_store_short_d16_hi v[144:145], v64 offset:64
	v_bfe_u32 v64, v17, 16, 1
	v_add3_u32 v64, v17, v64, s97
	flat_store_short_d16_hi v[144:145], v64 offset:80
	v_bfe_u32 v64, v18, 16, 1
	v_add3_u32 v64, v18, v64, s97
	flat_store_short_d16_hi v[144:145], v64 offset:96
	v_bfe_u32 v64, v19, 16, 1
	v_add3_u32 v64, v19, v64, s97
	flat_store_short_d16_hi v[144:145], v146
	flat_store_short_d16_hi v[144:145], v64 offset:112

.LBB0_245:
	s_andn2_b64 vcc, exec, s[0:1]
	s_cbranch_vccnz .LBB0_247
	v_ashrrev_i32_e32 v144, 5, v64
	v_ashrrev_i32_e32 v145, 31, v144
	v_lshlrev_b64 v[144:145], 12, v[144:145]
	v_lshl_add_u64 v[144:145], v[166:167], 0, v[144:145]
	v_lshlrev_b32_e32 v64, 1, v156
	v_lshl_add_u64 v[144:145], v[144:145], 0, v[64:65]
	v_bfe_u32 v64, v8, 16, 1
	v_lshl_add_u64 v[144:145], v[144:145], 0, s[52:53]
	v_add3_u32 v146, v8, v64, s97
	v_lshlrev_b32_e32 v64, 1, v158
	v_lshl_add_u64 v[144:145], v[144:145], 0, v[64:65]
	v_bfe_u32 v64, v9, 16, 1
	v_add3_u32 v64, v9, v64, s97
	flat_store_short_d16_hi v[144:145], v64 offset:24
	v_bfe_u32 v64, v10, 16, 1
	v_add3_u32 v64, v10, v64, s97
	flat_store_short_d16_hi v[144:145], v64 offset:40
	v_bfe_u32 v64, v11, 16, 1
	v_add3_u32 v64, v11, v64, s97
	flat_store_short_d16_hi v[144:145], v64 offset:56
	v_bfe_u32 v64, v0, 16, 1
	v_add3_u32 v64, v0, v64, s97
	flat_store_short_d16_hi v[144:145], v64 offset:72
	v_bfe_u32 v64, v1, 16, 1
	v_add3_u32 v64, v1, v64, s97
	flat_store_short_d16_hi v[144:145], v64 offset:88
	v_bfe_u32 v64, v2, 16, 1
	v_add3_u32 v64, v2, v64, s97
	flat_store_short_d16_hi v[144:145], v64 offset:104
	v_bfe_u32 v64, v3, 16, 1
	v_add3_u32 v64, v3, v64, s97
	flat_store_short_d16_hi v[144:145], v146 offset:8
	flat_store_short_d16_hi v[144:145], v64 offset:120

.LBB0_382:
	s_andn2_b64 vcc, exec, s[0:1]
	s_cbranch_vccnz .LBB0_551
	v_readlane_b32 s0, v254, 5
	v_readlane_b32 s1, v254, 6
	s_load_dwordx4 s[40:43], s[0:1], 0xa0
	s_load_dword s4, s[0:1], 0xb0
	v_mov_b32_e32 v0, v208
	v_readlane_b32 s5, v254, 0
	s_waitcnt lgkmcnt(0)
	v_ashrrev_i32_e32 v143, 6, v0
	s_waitcnt lgkmcnt(0)
	s_mov_b64 s[26:27], s[42:43]
	v_mov_b32_e32 v0, v208
	s_cmpk_gt_i32 s5, 0xff
	s_cbranch_scc1 .LBB0_390
	s_cmpk_lg_i32 s46, 0x100
	s_cbranch_scc1 .Lu_orig
	v_readfirstlane_b32 s12, v143
	v_and_b32_e32 v140, 63, v208
	v_lshlrev_b32_e32 v1, 4, v140
	v_and_b32_e32 v141, 15, v208
	v_bfe_u32 v140, v208, 4, 2
	v_lshlrev_b32_e32 v2, 6, v141
	v_lshl_add_u32 v2, v140, 4, v2
	v_mov_b32_e32 v3, v2
	v_lshlrev_b32_e32 v66, 6, v141
	v_lshl_add_u32 v66, v140, 3, v66
	v_add_u32_e32 v67, 0x1000, v66
	v_add_u32_e32 v140, 0x2000, v3
	s_lshr_b32 s8, s5, 6
	s_and_b32 s9, s5, 63
	s_lshl_b32 s0, s8, 23
	s_lshl_b32 s1, s9, 17
	s_add_i32 s0, s0, s1
	s_lshl_b32 s13, s12, 14
	s_add_i32 s0, s0, s13
	s_add_i32 s0, s0, 0x10d00000
	s_add_u32 s0, s26, s0
	s_addc_u32 s1, s27, 0
	s_add_i32 m0, s13, 0
	s_nop 0
	global_load_lds_dwordx4 v3, s[0:1]
	s_add_i32 m0, s13, 1024
	s_add_u32 s0, s0, 0x400
	s_addc_u32 s1, s1, 0
	global_load_lds_dwordx4 v3, s[0:1]
	s_add_i32 m0, s13, 2048
	s_add_u32 s0, s0, 0x400
	s_addc_u32 s1, s1, 0
	global_load_lds_dwordx4 v3, s[0:1]
	s_add_i32 m0, s13, 3072
	s_add_u32 s0, s0, 0x400
	s_addc_u32 s1, s1, 0
	global_load_lds_dwordx4 v3, s[0:1]
	s_add_i32 m0, s13, 4096
	s_add_u32 s0, s0, 0x400
	s_addc_u32 s1, s1, 0
	global_load_lds_dwordx4 v3, s[0:1]
	s_add_i32 m0, s13, 5120
	s_add_u32 s0, s0, 0x400
	s_addc_u32 s1, s1, 0
	global_load_lds_dwordx4 v3, s[0:1]
	s_add_i32 m0, s13, 6144
	s_add_u32 s0, s0, 0x400
	s_addc_u32 s1, s1, 0
	global_load_lds_dwordx4 v3, s[0:1]
	s_add_i32 m0, s13, 7168
	s_add_u32 s0, s0, 0x400
	s_addc_u32 s1, s1, 0
	global_load_lds_dwordx4 v3, s[0:1]
	s_add_i32 m0, s13, 8192
	s_add_u32 s0, s0, 0x400
	s_addc_u32 s1, s1, 0
	global_load_lds_dwordx4 v3, s[0:1]
	s_add_i32 m0, s13, 9216
	s_add_u32 s0, s0, 0x400
	s_addc_u32 s1, s1, 0
	global_load_lds_dwordx4 v3, s[0:1]
	s_add_i32 m0, s13, 10240
	s_add_u32 s0, s0, 0x400
	s_addc_u32 s1, s1, 0
	global_load_lds_dwordx4 v3, s[0:1]
	s_add_i32 m0, s13, 11264
	s_add_u32 s0, s0, 0x400
	s_addc_u32 s1, s1, 0
	global_load_lds_dwordx4 v3, s[0:1]
	s_add_i32 m0, s13, 12288
	s_add_u32 s0, s0, 0x400
	s_addc_u32 s1, s1, 0
	global_load_lds_dwordx4 v3, s[0:1]
	s_add_i32 m0, s13, 13312
	s_add_u32 s0, s0, 0x400
	s_addc_u32 s1, s1, 0
	global_load_lds_dwordx4 v3, s[0:1]
	s_add_i32 m0, s13, 14336
	s_add_u32 s0, s0, 0x400
	s_addc_u32 s1, s1, 0
	global_load_lds_dwordx4 v3, s[0:1]
	s_add_i32 m0, s13, 15360
	s_add_u32 s0, s0, 0x400
	s_addc_u32 s1, s1, 0
	global_load_lds_dwordx4 v3, s[0:1]
	s_lshl_b32 s2, s8, 24
	s_lshl_b32 s3, s9, 18
	s_add_i32 s2, s2, s3
	s_add_i32 s2, s2, 0x12d00000
	s_add_u32 s10, s26, s2
	s_addc_u32 s11, s27, 0
	s_lshl_b32 s2, s8, 6
	s_add_i32 s2, s2, s9
	s_lshl_b32 s2, s2, 18
	s_add_i32 s2, s2, 0x2d00000
	s_waitcnt vmcnt(0)
	s_add_u32 s0, s26, s2
	s_addc_u32 s1, s27, 0
	s_barrier
	s_lshl_b32 s8, s12, 10
	s_add_u32 s2, s10, s8
	s_addc_u32 s3, s11, 0
	s_lshl_b32 s8, s12, 13
	s_add_u32 s6, s0, s8
	s_addc_u32 s7, s1, 0
	v_mov_b32_e32 v4, 0
	v_mov_b32_e32 v5, 0
	v_mov_b32_e32 v6, 0
	v_mov_b32_e32 v7, 0
	v_mov_b32_e32 v8, 0
	v_mov_b32_e32 v9, 0
	v_mov_b32_e32 v10, 0
	v_mov_b32_e32 v11, 0
	v_mov_b32_e32 v12, 0
	v_mov_b32_e32 v13, 0
	v_mov_b32_e32 v14, 0
	v_mov_b32_e32 v15, 0
	v_mov_b32_e32 v16, 0
	v_mov_b32_e32 v17, 0
	v_mov_b32_e32 v18, 0
	v_mov_b32_e32 v19, 0
	v_mov_b32_e32 v20, 0
	v_mov_b32_e32 v21, 0
	v_mov_b32_e32 v22, 0
	v_mov_b32_e32 v23, 0
	v_mov_b32_e32 v24, 0
	v_mov_b32_e32 v25, 0
	v_mov_b32_e32 v26, 0
	v_mov_b32_e32 v27, 0
	v_mov_b32_e32 v28, 0
	v_mov_b32_e32 v29, 0
	v_mov_b32_e32 v30, 0
	v_mov_b32_e32 v31, 0
	v_mov_b32_e32 v32, 0
	v_mov_b32_e32 v33, 0
	v_mov_b32_e32 v34, 0
	v_mov_b32_e32 v35, 0
	v_mov_b32_e32 v36, 0
	v_mov_b32_e32 v37, 0
	v_mov_b32_e32 v38, 0
	v_mov_b32_e32 v39, 0
	v_mov_b32_e32 v40, 0
	v_mov_b32_e32 v41, 0
	v_mov_b32_e32 v42, 0
	v_mov_b32_e32 v43, 0
	v_mov_b32_e32 v44, 0
	v_mov_b32_e32 v45, 0
	v_mov_b32_e32 v46, 0
	v_mov_b32_e32 v47, 0
	v_mov_b32_e32 v48, 0
	v_mov_b32_e32 v49, 0
	v_mov_b32_e32 v50, 0
	v_mov_b32_e32 v51, 0
	v_mov_b32_e32 v52, 0
	v_mov_b32_e32 v53, 0
	v_mov_b32_e32 v54, 0
	v_mov_b32_e32 v55, 0
	v_mov_b32_e32 v56, 0
	v_mov_b32_e32 v57, 0
	v_mov_b32_e32 v58, 0
	v_mov_b32_e32 v59, 0
	v_mov_b32_e32 v60, 0
	v_mov_b32_e32 v61, 0
	v_mov_b32_e32 v62, 0
	v_mov_b32_e32 v63, 0
	v_mov_b32_e32 v68, 0
	v_mov_b32_e32 v69, 0
	v_mov_b32_e32 v70, 0
	v_mov_b32_e32 v71, 0
	v_mov_b32_e32 v72, 0
	v_mov_b32_e32 v73, 0
	v_mov_b32_e32 v74, 0
	v_mov_b32_e32 v75, 0
	v_mov_b32_e32 v76, 0
	v_mov_b32_e32 v77, 0
	v_mov_b32_e32 v78, 0
	v_mov_b32_e32 v79, 0
	v_mov_b32_e32 v80, 0
	v_mov_b32_e32 v81, 0
	v_mov_b32_e32 v82, 0
	v_mov_b32_e32 v83, 0
	v_mov_b32_e32 v84, 0
	v_mov_b32_e32 v85, 0
	v_mov_b32_e32 v86, 0
	v_mov_b32_e32 v87, 0
	v_mov_b32_e32 v88, 0
	v_mov_b32_e32 v89, 0
	v_mov_b32_e32 v90, 0
	v_mov_b32_e32 v91, 0
	v_mov_b32_e32 v92, 0
	v_mov_b32_e32 v93, 0
	v_mov_b32_e32 v94, 0
	v_mov_b32_e32 v95, 0
	v_mov_b32_e32 v96, 0
	v_mov_b32_e32 v97, 0
	v_mov_b32_e32 v98, 0
	v_mov_b32_e32 v99, 0
	v_mov_b32_e32 v100, 0
	v_mov_b32_e32 v101, 0
	v_mov_b32_e32 v102, 0
	v_mov_b32_e32 v103, 0
	v_mov_b32_e32 v104, 0
	v_mov_b32_e32 v105, 0
	v_mov_b32_e32 v106, 0
	v_mov_b32_e32 v107, 0
	v_mov_b32_e32 v108, 0
	v_mov_b32_e32 v109, 0
	v_mov_b32_e32 v110, 0
	v_mov_b32_e32 v111, 0
	v_mov_b32_e32 v112, 0
	v_mov_b32_e32 v113, 0
	v_mov_b32_e32 v114, 0
	v_mov_b32_e32 v115, 0
	v_mov_b32_e32 v116, 0
	v_mov_b32_e32 v117, 0
	v_mov_b32_e32 v118, 0
	v_mov_b32_e32 v119, 0
	v_mov_b32_e32 v120, 0
	v_mov_b32_e32 v121, 0
	v_mov_b32_e32 v122, 0
	v_mov_b32_e32 v123, 0
	v_mov_b32_e32 v124, 0
	v_mov_b32_e32 v125, 0
	v_mov_b32_e32 v126, 0
	v_mov_b32_e32 v127, 0
	v_mov_b32_e32 v128, 0
	v_mov_b32_e32 v129, 0
	v_mov_b32_e32 v130, 0
	v_mov_b32_e32 v131, 0
	v_mov_b32_e32 v132, 0
	v_mov_b32_e32 v133, 0
	v_mov_b32_e32 v134, 0
	v_mov_b32_e32 v135, 0
	global_load_dwordx4 v[136:139], v3, s[2:3]
	global_load_dwordx4 v[148:151], v140, s[2:3]
	v_mov_b32_e32 v141, v1
	s_mov_b32 s9, 4
.Lu_loop0:
	s_add_u32 s2, s2, 0x8000
	s_addc_u32 s3, s3, 0
	global_load_dwordx4 v[152:155], v3, s[2:3]
	global_load_dwordx4 v[156:159], v140, s[2:3]
	ds_read_b128 v[160:163], v141 offset:0
	ds_read_b128 v[164:167], v141 offset:1024
	ds_read_b128 v[168:171], v141 offset:2048
	s_waitcnt vmcnt(2)
	s_waitcnt lgkmcnt(2)
	v_mfma_f32_16x16x32_bf16 v[4:7], v[160:163], v[136:139], v[4:7]
	v_mfma_f32_16x16x32_bf16 v[72:75], v[160:163], v[148:151], v[72:75]
	ds_read_b128 v[160:163], v141 offset:3072
	s_waitcnt lgkmcnt(2)
	v_mfma_f32_16x16x32_bf16 v[8:11], v[164:167], v[136:139], v[8:11]
	v_mfma_f32_16x16x32_bf16 v[76:79], v[164:167], v[148:151], v[76:79]
	ds_read_b128 v[164:167], v141 offset:4096
	s_waitcnt lgkmcnt(2)
	v_mfma_f32_16x16x32_bf16 v[12:15], v[168:171], v[136:139], v[12:15]
	v_mfma_f32_16x16x32_bf16 v[80:83], v[168:171], v[148:151], v[80:83]
	ds_read_b128 v[168:171], v141 offset:5120
	s_waitcnt lgkmcnt(2)
	v_mfma_f32_16x16x32_bf16 v[16:19], v[160:163], v[136:139], v[16:19]
	v_mfma_f32_16x16x32_bf16 v[84:87], v[160:163], v[148:151], v[84:87]
	ds_read_b128 v[160:163], v141 offset:6144
	s_waitcnt lgkmcnt(2)
	v_mfma_f32_16x16x32_bf16 v[20:23], v[164:167], v[136:139], v[20:23]
	v_mfma_f32_16x16x32_bf16 v[88:91], v[164:167], v[148:151], v[88:91]
	ds_read_b128 v[164:167], v141 offset:7168
	s_waitcnt lgkmcnt(2)
	v_mfma_f32_16x16x32_bf16 v[24:27], v[168:171], v[136:139], v[24:27]
	v_mfma_f32_16x16x32_bf16 v[92:95], v[168:171], v[148:151], v[92:95]
	ds_read_b128 v[168:171], v141 offset:8192
	s_waitcnt lgkmcnt(2)
	v_mfma_f32_16x16x32_bf16 v[28:31], v[160:163], v[136:139], v[28:31]
	v_mfma_f32_16x16x32_bf16 v[96:99], v[160:163], v[148:151], v[96:99]
	ds_read_b128 v[160:163], v141 offset:9216
	s_waitcnt lgkmcnt(2)
	v_mfma_f32_16x16x32_bf16 v[32:35], v[164:167], v[136:139], v[32:35]
	v_mfma_f32_16x16x32_bf16 v[100:103], v[164:167], v[148:151], v[100:103]
	ds_read_b128 v[164:167], v141 offset:10240
	s_waitcnt lgkmcnt(2)
	v_mfma_f32_16x16x32_bf16 v[36:39], v[168:171], v[136:139], v[36:39]
	v_mfma_f32_16x16x32_bf16 v[104:107], v[168:171], v[148:151], v[104:107]
	ds_read_b128 v[168:171], v141 offset:11264
	s_waitcnt lgkmcnt(2)
	v_mfma_f32_16x16x32_bf16 v[40:43], v[160:163], v[136:139], v[40:43]
	v_mfma_f32_16x16x32_bf16 v[108:111], v[160:163], v[148:151], v[108:111]
	ds_read_b128 v[160:163], v141 offset:12288
	s_waitcnt lgkmcnt(2)
	v_mfma_f32_16x16x32_bf16 v[44:47], v[164:167], v[136:139], v[44:47]
	v_mfma_f32_16x16x32_bf16 v[112:115], v[164:167], v[148:151], v[112:115]
	ds_read_b128 v[164:167], v141 offset:13312
	s_waitcnt lgkmcnt(2)
	v_mfma_f32_16x16x32_bf16 v[48:51], v[168:171], v[136:139], v[48:51]
	v_mfma_f32_16x16x32_bf16 v[116:119], v[168:171], v[148:151], v[116:119]
	ds_read_b128 v[168:171], v141 offset:14336
	s_waitcnt lgkmcnt(2)
	v_mfma_f32_16x16x32_bf16 v[52:55], v[160:163], v[136:139], v[52:55]
	v_mfma_f32_16x16x32_bf16 v[120:123], v[160:163], v[148:151], v[120:123]
	ds_read_b128 v[160:163], v141 offset:15360
	s_waitcnt lgkmcnt(2)
	v_mfma_f32_16x16x32_bf16 v[56:59], v[164:167], v[136:139], v[56:59]
	v_mfma_f32_16x16x32_bf16 v[124:127], v[164:167], v[148:151], v[124:127]
	s_waitcnt lgkmcnt(1)
	v_mfma_f32_16x16x32_bf16 v[60:63], v[168:171], v[136:139], v[60:63]
	v_mfma_f32_16x16x32_bf16 v[128:131], v[168:171], v[148:151], v[128:131]
	s_waitcnt lgkmcnt(0)
	v_mfma_f32_16x16x32_bf16 v[68:71], v[160:163], v[136:139], v[68:71]
	v_mfma_f32_16x16x32_bf16 v[132:135], v[160:163], v[148:151], v[132:135]
	v_add_u32_e32 v141, 0x4000, v141
	s_add_u32 s2, s2, 0x8000
	s_addc_u32 s3, s3, 0
	global_load_dwordx4 v[136:139], v3, s[2:3]
	global_load_dwordx4 v[148:151], v140, s[2:3]
	ds_read_b128 v[160:163], v141 offset:0
	ds_read_b128 v[164:167], v141 offset:1024
	ds_read_b128 v[168:171], v141 offset:2048
	s_waitcnt vmcnt(2)
	s_waitcnt lgkmcnt(2)
	v_mfma_f32_16x16x32_bf16 v[4:7], v[160:163], v[152:155], v[4:7]
	v_mfma_f32_16x16x32_bf16 v[72:75], v[160:163], v[156:159], v[72:75]
	ds_read_b128 v[160:163], v141 offset:3072
	s_waitcnt lgkmcnt(2)
	v_mfma_f32_16x16x32_bf16 v[8:11], v[164:167], v[152:155], v[8:11]
	v_mfma_f32_16x16x32_bf16 v[76:79], v[164:167], v[156:159], v[76:79]
	ds_read_b128 v[164:167], v141 offset:4096
	s_waitcnt lgkmcnt(2)
	v_mfma_f32_16x16x32_bf16 v[12:15], v[168:171], v[152:155], v[12:15]
	v_mfma_f32_16x16x32_bf16 v[80:83], v[168:171], v[156:159], v[80:83]
	ds_read_b128 v[168:171], v141 offset:5120
	s_waitcnt lgkmcnt(2)
	v_mfma_f32_16x16x32_bf16 v[16:19], v[160:163], v[152:155], v[16:19]
	v_mfma_f32_16x16x32_bf16 v[84:87], v[160:163], v[156:159], v[84:87]
	ds_read_b128 v[160:163], v141 offset:6144
	s_waitcnt lgkmcnt(2)
	v_mfma_f32_16x16x32_bf16 v[20:23], v[164:167], v[152:155], v[20:23]
	v_mfma_f32_16x16x32_bf16 v[88:91], v[164:167], v[156:159], v[88:91]
	ds_read_b128 v[164:167], v141 offset:7168
	s_waitcnt lgkmcnt(2)
	v_mfma_f32_16x16x32_bf16 v[24:27], v[168:171], v[152:155], v[24:27]
	v_mfma_f32_16x16x32_bf16 v[92:95], v[168:171], v[156:159], v[92:95]
	ds_read_b128 v[168:171], v141 offset:8192
	s_waitcnt lgkmcnt(2)
	v_mfma_f32_16x16x32_bf16 v[28:31], v[160:163], v[152:155], v[28:31]
	v_mfma_f32_16x16x32_bf16 v[96:99], v[160:163], v[156:159], v[96:99]
	ds_read_b128 v[160:163], v141 offset:9216
	s_waitcnt lgkmcnt(2)
	v_mfma_f32_16x16x32_bf16 v[32:35], v[164:167], v[152:155], v[32:35]
	v_mfma_f32_16x16x32_bf16 v[100:103], v[164:167], v[156:159], v[100:103]
	ds_read_b128 v[164:167], v141 offset:10240
	s_waitcnt lgkmcnt(2)
	v_mfma_f32_16x16x32_bf16 v[36:39], v[168:171], v[152:155], v[36:39]
	v_mfma_f32_16x16x32_bf16 v[104:107], v[168:171], v[156:159], v[104:107]
	ds_read_b128 v[168:171], v141 offset:11264
	s_waitcnt lgkmcnt(2)
	v_mfma_f32_16x16x32_bf16 v[40:43], v[160:163], v[152:155], v[40:43]
	v_mfma_f32_16x16x32_bf16 v[108:111], v[160:163], v[156:159], v[108:111]
	ds_read_b128 v[160:163], v141 offset:12288
	s_waitcnt lgkmcnt(2)
	v_mfma_f32_16x16x32_bf16 v[44:47], v[164:167], v[152:155], v[44:47]
	v_mfma_f32_16x16x32_bf16 v[112:115], v[164:167], v[156:159], v[112:115]
	ds_read_b128 v[164:167], v141 offset:13312
	s_waitcnt lgkmcnt(2)
	v_mfma_f32_16x16x32_bf16 v[48:51], v[168:171], v[152:155], v[48:51]
	v_mfma_f32_16x16x32_bf16 v[116:119], v[168:171], v[156:159], v[116:119]
	ds_read_b128 v[168:171], v141 offset:14336
	s_waitcnt lgkmcnt(2)
	v_mfma_f32_16x16x32_bf16 v[52:55], v[160:163], v[152:155], v[52:55]
	v_mfma_f32_16x16x32_bf16 v[120:123], v[160:163], v[156:159], v[120:123]
	ds_read_b128 v[160:163], v141 offset:15360
	s_waitcnt lgkmcnt(2)
	v_mfma_f32_16x16x32_bf16 v[56:59], v[164:167], v[152:155], v[56:59]
	v_mfma_f32_16x16x32_bf16 v[124:127], v[164:167], v[156:159], v[124:127]
	s_waitcnt lgkmcnt(1)
	v_mfma_f32_16x16x32_bf16 v[60:63], v[168:171], v[152:155], v[60:63]
	v_mfma_f32_16x16x32_bf16 v[128:131], v[168:171], v[156:159], v[128:131]
	s_waitcnt lgkmcnt(0)
	v_mfma_f32_16x16x32_bf16 v[68:71], v[160:163], v[152:155], v[68:71]
	v_mfma_f32_16x16x32_bf16 v[132:135], v[160:163], v[156:159], v[132:135]
	v_add_u32_e32 v141, 0x4000, v141
	s_add_i32 s9, s9, -1
	s_cmp_lg_u32 s9, 0
	s_cbranch_scc1 .Lu_loop0
	s_waitcnt vmcnt(0)
	s_nop 7
	v_cvt_pk_bf16_f32 v4, v4, v5
	v_cvt_pk_bf16_f32 v5, v6, v7
	global_store_dwordx2 v66, v[4:5], s[6:7] offset:0
	v_cvt_pk_bf16_f32 v8, v8, v9
	v_cvt_pk_bf16_f32 v9, v10, v11
	global_store_dwordx2 v66, v[8:9], s[6:7] offset:32
	v_cvt_pk_bf16_f32 v12, v12, v13
	v_cvt_pk_bf16_f32 v13, v14, v15
	global_store_dwordx2 v66, v[12:13], s[6:7] offset:1024
	v_cvt_pk_bf16_f32 v16, v16, v17
	v_cvt_pk_bf16_f32 v17, v18, v19
	global_store_dwordx2 v66, v[16:17], s[6:7] offset:1056
	v_cvt_pk_bf16_f32 v20, v20, v21
	v_cvt_pk_bf16_f32 v21, v22, v23
	global_store_dwordx2 v66, v[20:21], s[6:7] offset:2048
	v_cvt_pk_bf16_f32 v24, v24, v25
	v_cvt_pk_bf16_f32 v25, v26, v27
	global_store_dwordx2 v66, v[24:25], s[6:7] offset:2080
	v_cvt_pk_bf16_f32 v28, v28, v29
	v_cvt_pk_bf16_f32 v29, v30, v31
	global_store_dwordx2 v66, v[28:29], s[6:7] offset:3072
	v_cvt_pk_bf16_f32 v32, v32, v33
	v_cvt_pk_bf16_f32 v33, v34, v35
	global_store_dwordx2 v66, v[32:33], s[6:7] offset:3104
	v_cvt_pk_bf16_f32 v36, v36, v37
	v_cvt_pk_bf16_f32 v37, v38, v39
	global_store_dwordx2 v67, v[36:37], s[6:7] offset:0
	v_cvt_pk_bf16_f32 v40, v40, v41
	v_cvt_pk_bf16_f32 v41, v42, v43
	global_store_dwordx2 v67, v[40:41], s[6:7] offset:32
	v_cvt_pk_bf16_f32 v44, v44, v45
	v_cvt_pk_bf16_f32 v45, v46, v47
	global_store_dwordx2 v67, v[44:45], s[6:7] offset:1024
	v_cvt_pk_bf16_f32 v48, v48, v49
	v_cvt_pk_bf16_f32 v49, v50, v51
	global_store_dwordx2 v67, v[48:49], s[6:7] offset:1056
	v_cvt_pk_bf16_f32 v52, v52, v53
	v_cvt_pk_bf16_f32 v53, v54, v55
	global_store_dwordx2 v67, v[52:53], s[6:7] offset:2048
	v_cvt_pk_bf16_f32 v56, v56, v57
	v_cvt_pk_bf16_f32 v57, v58, v59
	global_store_dwordx2 v67, v[56:57], s[6:7] offset:2080
	v_cvt_pk_bf16_f32 v60, v60, v61
	v_cvt_pk_bf16_f32 v61, v62, v63
	global_store_dwordx2 v67, v[60:61], s[6:7] offset:3072
	v_cvt_pk_bf16_f32 v68, v68, v69
	v_cvt_pk_bf16_f32 v69, v70, v71
	global_store_dwordx2 v67, v[68:69], s[6:7] offset:3104
	s_add_u32 s6, s6, 0x10000
	s_addc_u32 s7, s7, 0
	v_cvt_pk_bf16_f32 v72, v72, v73
	v_cvt_pk_bf16_f32 v73, v74, v75
	global_store_dwordx2 v66, v[72:73], s[6:7] offset:0
	v_cvt_pk_bf16_f32 v76, v76, v77
	v_cvt_pk_bf16_f32 v77, v78, v79
	global_store_dwordx2 v66, v[76:77], s[6:7] offset:32
	v_cvt_pk_bf16_f32 v80, v80, v81
	v_cvt_pk_bf16_f32 v81, v82, v83
	global_store_dwordx2 v66, v[80:81], s[6:7] offset:1024
	v_cvt_pk_bf16_f32 v84, v84, v85
	v_cvt_pk_bf16_f32 v85, v86, v87
	global_store_dwordx2 v66, v[84:85], s[6:7] offset:1056
	v_cvt_pk_bf16_f32 v88, v88, v89
	v_cvt_pk_bf16_f32 v89, v90, v91
	global_store_dwordx2 v66, v[88:89], s[6:7] offset:2048
	v_cvt_pk_bf16_f32 v92, v92, v93
	v_cvt_pk_bf16_f32 v93, v94, v95
	global_store_dwordx2 v66, v[92:93], s[6:7] offset:2080
	v_cvt_pk_bf16_f32 v96, v96, v97
	v_cvt_pk_bf16_f32 v97, v98, v99
	global_store_dwordx2 v66, v[96:97], s[6:7] offset:3072
	v_cvt_pk_bf16_f32 v100, v100, v101
	v_cvt_pk_bf16_f32 v101, v102, v103
	global_store_dwordx2 v66, v[100:101], s[6:7] offset:3104
	v_cvt_pk_bf16_f32 v104, v104, v105
	v_cvt_pk_bf16_f32 v105, v106, v107
	global_store_dwordx2 v67, v[104:105], s[6:7] offset:0
	v_cvt_pk_bf16_f32 v108, v108, v109
	v_cvt_pk_bf16_f32 v109, v110, v111
	global_store_dwordx2 v67, v[108:109], s[6:7] offset:32
	v_cvt_pk_bf16_f32 v112, v112, v113
	v_cvt_pk_bf16_f32 v113, v114, v115
	global_store_dwordx2 v67, v[112:113], s[6:7] offset:1024
	v_cvt_pk_bf16_f32 v116, v116, v117
	v_cvt_pk_bf16_f32 v117, v118, v119
	global_store_dwordx2 v67, v[116:117], s[6:7] offset:1056
	v_cvt_pk_bf16_f32 v120, v120, v121
	v_cvt_pk_bf16_f32 v121, v122, v123
	global_store_dwordx2 v67, v[120:121], s[6:7] offset:2048
	v_cvt_pk_bf16_f32 v124, v124, v125
	v_cvt_pk_bf16_f32 v125, v126, v127
	global_store_dwordx2 v67, v[124:125], s[6:7] offset:2080
	v_cvt_pk_bf16_f32 v128, v128, v129
	v_cvt_pk_bf16_f32 v129, v130, v131
	global_store_dwordx2 v67, v[128:129], s[6:7] offset:3072
	v_cvt_pk_bf16_f32 v132, v132, v133
	v_cvt_pk_bf16_f32 v133, v134, v135
	global_store_dwordx2 v67, v[132:133], s[6:7] offset:3104
	s_lshl_b32 s8, s12, 10
	s_add_i32 s8, s8, 0x4000
	s_add_u32 s2, s10, s8
	s_addc_u32 s3, s11, 0
	s_lshl_b32 s8, s12, 13
	s_add_i32 s8, s8, 0x20000
	s_add_u32 s6, s0, s8
	s_addc_u32 s7, s1, 0
	v_mov_b32_e32 v4, 0
	v_mov_b32_e32 v5, 0
	v_mov_b32_e32 v6, 0
	v_mov_b32_e32 v7, 0
	v_mov_b32_e32 v8, 0
	v_mov_b32_e32 v9, 0
	v_mov_b32_e32 v10, 0
	v_mov_b32_e32 v11, 0
	v_mov_b32_e32 v12, 0
	v_mov_b32_e32 v13, 0
	v_mov_b32_e32 v14, 0
	v_mov_b32_e32 v15, 0
	v_mov_b32_e32 v16, 0
	v_mov_b32_e32 v17, 0
	v_mov_b32_e32 v18, 0
	v_mov_b32_e32 v19, 0
	v_mov_b32_e32 v20, 0
	v_mov_b32_e32 v21, 0
	v_mov_b32_e32 v22, 0
	v_mov_b32_e32 v23, 0
	v_mov_b32_e32 v24, 0
	v_mov_b32_e32 v25, 0
	v_mov_b32_e32 v26, 0
	v_mov_b32_e32 v27, 0
	v_mov_b32_e32 v28, 0
	v_mov_b32_e32 v29, 0
	v_mov_b32_e32 v30, 0
	v_mov_b32_e32 v31, 0
	v_mov_b32_e32 v32, 0
	v_mov_b32_e32 v33, 0
	v_mov_b32_e32 v34, 0
	v_mov_b32_e32 v35, 0
	v_mov_b32_e32 v36, 0
	v_mov_b32_e32 v37, 0
	v_mov_b32_e32 v38, 0
	v_mov_b32_e32 v39, 0
	v_mov_b32_e32 v40, 0
	v_mov_b32_e32 v41, 0
	v_mov_b32_e32 v42, 0
	v_mov_b32_e32 v43, 0
	v_mov_b32_e32 v44, 0
	v_mov_b32_e32 v45, 0
	v_mov_b32_e32 v46, 0
	v_mov_b32_e32 v47, 0
	v_mov_b32_e32 v48, 0
	v_mov_b32_e32 v49, 0
	v_mov_b32_e32 v50, 0
	v_mov_b32_e32 v51, 0
	v_mov_b32_e32 v52, 0
	v_mov_b32_e32 v53, 0
	v_mov_b32_e32 v54, 0
	v_mov_b32_e32 v55, 0
	v_mov_b32_e32 v56, 0
	v_mov_b32_e32 v57, 0
	v_mov_b32_e32 v58, 0
	v_mov_b32_e32 v59, 0
	v_mov_b32_e32 v60, 0
	v_mov_b32_e32 v61, 0
	v_mov_b32_e32 v62, 0
	v_mov_b32_e32 v63, 0
	v_mov_b32_e32 v68, 0
	v_mov_b32_e32 v69, 0
	v_mov_b32_e32 v70, 0
	v_mov_b32_e32 v71, 0
	v_mov_b32_e32 v72, 0
	v_mov_b32_e32 v73, 0
	v_mov_b32_e32 v74, 0
	v_mov_b32_e32 v75, 0
	v_mov_b32_e32 v76, 0
	v_mov_b32_e32 v77, 0
	v_mov_b32_e32 v78, 0
	v_mov_b32_e32 v79, 0
	v_mov_b32_e32 v80, 0
	v_mov_b32_e32 v81, 0
	v_mov_b32_e32 v82, 0
	v_mov_b32_e32 v83, 0
	v_mov_b32_e32 v84, 0
	v_mov_b32_e32 v85, 0
	v_mov_b32_e32 v86, 0
	v_mov_b32_e32 v87, 0
	v_mov_b32_e32 v88, 0
	v_mov_b32_e32 v89, 0
	v_mov_b32_e32 v90, 0
	v_mov_b32_e32 v91, 0
	v_mov_b32_e32 v92, 0
	v_mov_b32_e32 v93, 0
	v_mov_b32_e32 v94, 0
	v_mov_b32_e32 v95, 0
	v_mov_b32_e32 v96, 0
	v_mov_b32_e32 v97, 0
	v_mov_b32_e32 v98, 0
	v_mov_b32_e32 v99, 0
	v_mov_b32_e32 v100, 0
	v_mov_b32_e32 v101, 0
	v_mov_b32_e32 v102, 0
	v_mov_b32_e32 v103, 0
	v_mov_b32_e32 v104, 0
	v_mov_b32_e32 v105, 0
	v_mov_b32_e32 v106, 0
	v_mov_b32_e32 v107, 0
	v_mov_b32_e32 v108, 0
	v_mov_b32_e32 v109, 0
	v_mov_b32_e32 v110, 0
	v_mov_b32_e32 v111, 0
	v_mov_b32_e32 v112, 0
	v_mov_b32_e32 v113, 0
	v_mov_b32_e32 v114, 0
	v_mov_b32_e32 v115, 0
	v_mov_b32_e32 v116, 0
	v_mov_b32_e32 v117, 0
	v_mov_b32_e32 v118, 0
	v_mov_b32_e32 v119, 0
	v_mov_b32_e32 v120, 0
	v_mov_b32_e32 v121, 0
	v_mov_b32_e32 v122, 0
	v_mov_b32_e32 v123, 0
	v_mov_b32_e32 v124, 0
	v_mov_b32_e32 v125, 0
	v_mov_b32_e32 v126, 0
	v_mov_b32_e32 v127, 0
	v_mov_b32_e32 v128, 0
	v_mov_b32_e32 v129, 0
	v_mov_b32_e32 v130, 0
	v_mov_b32_e32 v131, 0
	v_mov_b32_e32 v132, 0
	v_mov_b32_e32 v133, 0
	v_mov_b32_e32 v134, 0
	v_mov_b32_e32 v135, 0
	global_load_dwordx4 v[136:139], v3, s[2:3]
	global_load_dwordx4 v[148:151], v140, s[2:3]
	v_mov_b32_e32 v141, v1
	s_mov_b32 s9, 4
.Lu_loop1:
	s_add_u32 s2, s2, 0x8000
	s_addc_u32 s3, s3, 0
	global_load_dwordx4 v[152:155], v3, s[2:3]
	global_load_dwordx4 v[156:159], v140, s[2:3]
	ds_read_b128 v[160:163], v141 offset:0
	ds_read_b128 v[164:167], v141 offset:1024
	ds_read_b128 v[168:171], v141 offset:2048
	s_waitcnt vmcnt(2)
	s_waitcnt lgkmcnt(2)
	v_mfma_f32_16x16x32_bf16 v[4:7], v[160:163], v[136:139], v[4:7]
	v_mfma_f32_16x16x32_bf16 v[72:75], v[160:163], v[148:151], v[72:75]
	ds_read_b128 v[160:163], v141 offset:3072
	s_waitcnt lgkmcnt(2)
	v_mfma_f32_16x16x32_bf16 v[8:11], v[164:167], v[136:139], v[8:11]
	v_mfma_f32_16x16x32_bf16 v[76:79], v[164:167], v[148:151], v[76:79]
	ds_read_b128 v[164:167], v141 offset:4096
	s_waitcnt lgkmcnt(2)
	v_mfma_f32_16x16x32_bf16 v[12:15], v[168:171], v[136:139], v[12:15]
	v_mfma_f32_16x16x32_bf16 v[80:83], v[168:171], v[148:151], v[80:83]
	ds_read_b128 v[168:171], v141 offset:5120
	s_waitcnt lgkmcnt(2)
	v_mfma_f32_16x16x32_bf16 v[16:19], v[160:163], v[136:139], v[16:19]
	v_mfma_f32_16x16x32_bf16 v[84:87], v[160:163], v[148:151], v[84:87]
	ds_read_b128 v[160:163], v141 offset:6144
	s_waitcnt lgkmcnt(2)
	v_mfma_f32_16x16x32_bf16 v[20:23], v[164:167], v[136:139], v[20:23]
	v_mfma_f32_16x16x32_bf16 v[88:91], v[164:167], v[148:151], v[88:91]
	ds_read_b128 v[164:167], v141 offset:7168
	s_waitcnt lgkmcnt(2)
	v_mfma_f32_16x16x32_bf16 v[24:27], v[168:171], v[136:139], v[24:27]
	v_mfma_f32_16x16x32_bf16 v[92:95], v[168:171], v[148:151], v[92:95]
	ds_read_b128 v[168:171], v141 offset:8192
	s_waitcnt lgkmcnt(2)
	v_mfma_f32_16x16x32_bf16 v[28:31], v[160:163], v[136:139], v[28:31]
	v_mfma_f32_16x16x32_bf16 v[96:99], v[160:163], v[148:151], v[96:99]
	ds_read_b128 v[160:163], v141 offset:9216
	s_waitcnt lgkmcnt(2)
	v_mfma_f32_16x16x32_bf16 v[32:35], v[164:167], v[136:139], v[32:35]
	v_mfma_f32_16x16x32_bf16 v[100:103], v[164:167], v[148:151], v[100:103]
	ds_read_b128 v[164:167], v141 offset:10240
	s_waitcnt lgkmcnt(2)
	v_mfma_f32_16x16x32_bf16 v[36:39], v[168:171], v[136:139], v[36:39]
	v_mfma_f32_16x16x32_bf16 v[104:107], v[168:171], v[148:151], v[104:107]
	ds_read_b128 v[168:171], v141 offset:11264
	s_waitcnt lgkmcnt(2)
	v_mfma_f32_16x16x32_bf16 v[40:43], v[160:163], v[136:139], v[40:43]
	v_mfma_f32_16x16x32_bf16 v[108:111], v[160:163], v[148:151], v[108:111]
	ds_read_b128 v[160:163], v141 offset:12288
	s_waitcnt lgkmcnt(2)
	v_mfma_f32_16x16x32_bf16 v[44:47], v[164:167], v[136:139], v[44:47]
	v_mfma_f32_16x16x32_bf16 v[112:115], v[164:167], v[148:151], v[112:115]
	ds_read_b128 v[164:167], v141 offset:13312
	s_waitcnt lgkmcnt(2)
	v_mfma_f32_16x16x32_bf16 v[48:51], v[168:171], v[136:139], v[48:51]
	v_mfma_f32_16x16x32_bf16 v[116:119], v[168:171], v[148:151], v[116:119]
	ds_read_b128 v[168:171], v141 offset:14336
	s_waitcnt lgkmcnt(2)
	v_mfma_f32_16x16x32_bf16 v[52:55], v[160:163], v[136:139], v[52:55]
	v_mfma_f32_16x16x32_bf16 v[120:123], v[160:163], v[148:151], v[120:123]
	ds_read_b128 v[160:163], v141 offset:15360
	s_waitcnt lgkmcnt(2)
	v_mfma_f32_16x16x32_bf16 v[56:59], v[164:167], v[136:139], v[56:59]
	v_mfma_f32_16x16x32_bf16 v[124:127], v[164:167], v[148:151], v[124:127]
	s_waitcnt lgkmcnt(1)
	v_mfma_f32_16x16x32_bf16 v[60:63], v[168:171], v[136:139], v[60:63]
	v_mfma_f32_16x16x32_bf16 v[128:131], v[168:171], v[148:151], v[128:131]
	s_waitcnt lgkmcnt(0)
	v_mfma_f32_16x16x32_bf16 v[68:71], v[160:163], v[136:139], v[68:71]
	v_mfma_f32_16x16x32_bf16 v[132:135], v[160:163], v[148:151], v[132:135]
	v_add_u32_e32 v141, 0x4000, v141
	s_add_u32 s2, s2, 0x8000
	s_addc_u32 s3, s3, 0
	global_load_dwordx4 v[136:139], v3, s[2:3]
	global_load_dwordx4 v[148:151], v140, s[2:3]
	ds_read_b128 v[160:163], v141 offset:0
	ds_read_b128 v[164:167], v141 offset:1024
	ds_read_b128 v[168:171], v141 offset:2048
	s_waitcnt vmcnt(2)
	s_waitcnt lgkmcnt(2)
	v_mfma_f32_16x16x32_bf16 v[4:7], v[160:163], v[152:155], v[4:7]
	v_mfma_f32_16x16x32_bf16 v[72:75], v[160:163], v[156:159], v[72:75]
	ds_read_b128 v[160:163], v141 offset:3072
	s_waitcnt lgkmcnt(2)
	v_mfma_f32_16x16x32_bf16 v[8:11], v[164:167], v[152:155], v[8:11]
	v_mfma_f32_16x16x32_bf16 v[76:79], v[164:167], v[156:159], v[76:79]
	ds_read_b128 v[164:167], v141 offset:4096
	s_waitcnt lgkmcnt(2)
	v_mfma_f32_16x16x32_bf16 v[12:15], v[168:171], v[152:155], v[12:15]
	v_mfma_f32_16x16x32_bf16 v[80:83], v[168:171], v[156:159], v[80:83]
	ds_read_b128 v[168:171], v141 offset:5120
	s_waitcnt lgkmcnt(2)
	v_mfma_f32_16x16x32_bf16 v[16:19], v[160:163], v[152:155], v[16:19]
	v_mfma_f32_16x16x32_bf16 v[84:87], v[160:163], v[156:159], v[84:87]
	ds_read_b128 v[160:163], v141 offset:6144
	s_waitcnt lgkmcnt(2)
	v_mfma_f32_16x16x32_bf16 v[20:23], v[164:167], v[152:155], v[20:23]
	v_mfma_f32_16x16x32_bf16 v[88:91], v[164:167], v[156:159], v[88:91]
	ds_read_b128 v[164:167], v141 offset:7168
	s_waitcnt lgkmcnt(2)
	v_mfma_f32_16x16x32_bf16 v[24:27], v[168:171], v[152:155], v[24:27]
	v_mfma_f32_16x16x32_bf16 v[92:95], v[168:171], v[156:159], v[92:95]
	ds_read_b128 v[168:171], v141 offset:8192
	s_waitcnt lgkmcnt(2)
	v_mfma_f32_16x16x32_bf16 v[28:31], v[160:163], v[152:155], v[28:31]
	v_mfma_f32_16x16x32_bf16 v[96:99], v[160:163], v[156:159], v[96:99]
	ds_read_b128 v[160:163], v141 offset:9216
	s_waitcnt lgkmcnt(2)
	v_mfma_f32_16x16x32_bf16 v[32:35], v[164:167], v[152:155], v[32:35]
	v_mfma_f32_16x16x32_bf16 v[100:103], v[164:167], v[156:159], v[100:103]
	ds_read_b128 v[164:167], v141 offset:10240
	s_waitcnt lgkmcnt(2)
	v_mfma_f32_16x16x32_bf16 v[36:39], v[168:171], v[152:155], v[36:39]
	v_mfma_f32_16x16x32_bf16 v[104:107], v[168:171], v[156:159], v[104:107]
	ds_read_b128 v[168:171], v141 offset:11264
	s_waitcnt lgkmcnt(2)
	v_mfma_f32_16x16x32_bf16 v[40:43], v[160:163], v[152:155], v[40:43]
	v_mfma_f32_16x16x32_bf16 v[108:111], v[160:163], v[156:159], v[108:111]
	ds_read_b128 v[160:163], v141 offset:12288
	s_waitcnt lgkmcnt(2)
	v_mfma_f32_16x16x32_bf16 v[44:47], v[164:167], v[152:155], v[44:47]
	v_mfma_f32_16x16x32_bf16 v[112:115], v[164:167], v[156:159], v[112:115]
	ds_read_b128 v[164:167], v141 offset:13312
	s_waitcnt lgkmcnt(2)
	v_mfma_f32_16x16x32_bf16 v[48:51], v[168:171], v[152:155], v[48:51]
	v_mfma_f32_16x16x32_bf16 v[116:119], v[168:171], v[156:159], v[116:119]
	ds_read_b128 v[168:171], v141 offset:14336
	s_waitcnt lgkmcnt(2)
	v_mfma_f32_16x16x32_bf16 v[52:55], v[160:163], v[152:155], v[52:55]
	v_mfma_f32_16x16x32_bf16 v[120:123], v[160:163], v[156:159], v[120:123]
	ds_read_b128 v[160:163], v141 offset:15360
	s_waitcnt lgkmcnt(2)
	v_mfma_f32_16x16x32_bf16 v[56:59], v[164:167], v[152:155], v[56:59]
	v_mfma_f32_16x16x32_bf16 v[124:127], v[164:167], v[156:159], v[124:127]
	s_waitcnt lgkmcnt(1)
	v_mfma_f32_16x16x32_bf16 v[60:63], v[168:171], v[152:155], v[60:63]
	v_mfma_f32_16x16x32_bf16 v[128:131], v[168:171], v[156:159], v[128:131]
	s_waitcnt lgkmcnt(0)
	v_mfma_f32_16x16x32_bf16 v[68:71], v[160:163], v[152:155], v[68:71]
	v_mfma_f32_16x16x32_bf16 v[132:135], v[160:163], v[156:159], v[132:135]
	v_add_u32_e32 v141, 0x4000, v141
	s_add_i32 s9, s9, -1
	s_cmp_lg_u32 s9, 0
	s_cbranch_scc1 .Lu_loop1
	s_waitcnt vmcnt(0)
	s_nop 7
	v_cvt_pk_bf16_f32 v4, v4, v5
	v_cvt_pk_bf16_f32 v5, v6, v7
	global_store_dwordx2 v66, v[4:5], s[6:7] offset:0
	v_cvt_pk_bf16_f32 v8, v8, v9
	v_cvt_pk_bf16_f32 v9, v10, v11
	global_store_dwordx2 v66, v[8:9], s[6:7] offset:32
	v_cvt_pk_bf16_f32 v12, v12, v13
	v_cvt_pk_bf16_f32 v13, v14, v15
	global_store_dwordx2 v66, v[12:13], s[6:7] offset:1024
	v_cvt_pk_bf16_f32 v16, v16, v17
	v_cvt_pk_bf16_f32 v17, v18, v19
	global_store_dwordx2 v66, v[16:17], s[6:7] offset:1056
	v_cvt_pk_bf16_f32 v20, v20, v21
	v_cvt_pk_bf16_f32 v21, v22, v23
	global_store_dwordx2 v66, v[20:21], s[6:7] offset:2048
	v_cvt_pk_bf16_f32 v24, v24, v25
	v_cvt_pk_bf16_f32 v25, v26, v27
	global_store_dwordx2 v66, v[24:25], s[6:7] offset:2080
	v_cvt_pk_bf16_f32 v28, v28, v29
	v_cvt_pk_bf16_f32 v29, v30, v31
	global_store_dwordx2 v66, v[28:29], s[6:7] offset:3072
	v_cvt_pk_bf16_f32 v32, v32, v33
	v_cvt_pk_bf16_f32 v33, v34, v35
	global_store_dwordx2 v66, v[32:33], s[6:7] offset:3104
	v_cvt_pk_bf16_f32 v36, v36, v37
	v_cvt_pk_bf16_f32 v37, v38, v39
	global_store_dwordx2 v67, v[36:37], s[6:7] offset:0
	v_cvt_pk_bf16_f32 v40, v40, v41
	v_cvt_pk_bf16_f32 v41, v42, v43
	global_store_dwordx2 v67, v[40:41], s[6:7] offset:32
	v_cvt_pk_bf16_f32 v44, v44, v45
	v_cvt_pk_bf16_f32 v45, v46, v47
	global_store_dwordx2 v67, v[44:45], s[6:7] offset:1024
	v_cvt_pk_bf16_f32 v48, v48, v49
	v_cvt_pk_bf16_f32 v49, v50, v51
	global_store_dwordx2 v67, v[48:49], s[6:7] offset:1056
	v_cvt_pk_bf16_f32 v52, v52, v53
	v_cvt_pk_bf16_f32 v53, v54, v55
	global_store_dwordx2 v67, v[52:53], s[6:7] offset:2048
	v_cvt_pk_bf16_f32 v56, v56, v57
	v_cvt_pk_bf16_f32 v57, v58, v59
	global_store_dwordx2 v67, v[56:57], s[6:7] offset:2080
	v_cvt_pk_bf16_f32 v60, v60, v61
	v_cvt_pk_bf16_f32 v61, v62, v63
	global_store_dwordx2 v67, v[60:61], s[6:7] offset:3072
	v_cvt_pk_bf16_f32 v68, v68, v69
	v_cvt_pk_bf16_f32 v69, v70, v71
	global_store_dwordx2 v67, v[68:69], s[6:7] offset:3104
	s_add_u32 s6, s6, 0x10000
	s_addc_u32 s7, s7, 0
	v_cvt_pk_bf16_f32 v72, v72, v73
	v_cvt_pk_bf16_f32 v73, v74, v75
	global_store_dwordx2 v66, v[72:73], s[6:7] offset:0
	v_cvt_pk_bf16_f32 v76, v76, v77
	v_cvt_pk_bf16_f32 v77, v78, v79
	global_store_dwordx2 v66, v[76:77], s[6:7] offset:32
	v_cvt_pk_bf16_f32 v80, v80, v81
	v_cvt_pk_bf16_f32 v81, v82, v83
	global_store_dwordx2 v66, v[80:81], s[6:7] offset:1024
	v_cvt_pk_bf16_f32 v84, v84, v85
	v_cvt_pk_bf16_f32 v85, v86, v87
	global_store_dwordx2 v66, v[84:85], s[6:7] offset:1056
	v_cvt_pk_bf16_f32 v88, v88, v89
	v_cvt_pk_bf16_f32 v89, v90, v91
	global_store_dwordx2 v66, v[88:89], s[6:7] offset:2048
	v_cvt_pk_bf16_f32 v92, v92, v93
	v_cvt_pk_bf16_f32 v93, v94, v95
	global_store_dwordx2 v66, v[92:93], s[6:7] offset:2080
	v_cvt_pk_bf16_f32 v96, v96, v97
	v_cvt_pk_bf16_f32 v97, v98, v99
	global_store_dwordx2 v66, v[96:97], s[6:7] offset:3072
	v_cvt_pk_bf16_f32 v100, v100, v101
	v_cvt_pk_bf16_f32 v101, v102, v103
	global_store_dwordx2 v66, v[100:101], s[6:7] offset:3104
	v_cvt_pk_bf16_f32 v104, v104, v105
	v_cvt_pk_bf16_f32 v105, v106, v107
	global_store_dwordx2 v67, v[104:105], s[6:7] offset:0
	v_cvt_pk_bf16_f32 v108, v108, v109
	v_cvt_pk_bf16_f32 v109, v110, v111
	global_store_dwordx2 v67, v[108:109], s[6:7] offset:32
	v_cvt_pk_bf16_f32 v112, v112, v113
	v_cvt_pk_bf16_f32 v113, v114, v115
	global_store_dwordx2 v67, v[112:113], s[6:7] offset:1024
	v_cvt_pk_bf16_f32 v116, v116, v117
	v_cvt_pk_bf16_f32 v117, v118, v119
	global_store_dwordx2 v67, v[116:117], s[6:7] offset:1056
	v_cvt_pk_bf16_f32 v120, v120, v121
	v_cvt_pk_bf16_f32 v121, v122, v123
	global_store_dwordx2 v67, v[120:121], s[6:7] offset:2048
	v_cvt_pk_bf16_f32 v124, v124, v125
	v_cvt_pk_bf16_f32 v125, v126, v127
	global_store_dwordx2 v67, v[124:125], s[6:7] offset:2080
	v_cvt_pk_bf16_f32 v128, v128, v129
	v_cvt_pk_bf16_f32 v129, v130, v131
	global_store_dwordx2 v67, v[128:129], s[6:7] offset:3072
	v_cvt_pk_bf16_f32 v132, v132, v133
	v_cvt_pk_bf16_f32 v133, v134, v135
	global_store_dwordx2 v67, v[132:133], s[6:7] offset:3104
	s_waitcnt lgkmcnt(0)
	s_barrier
	s_branch .LBB0_390
.Lu_orig:
	v_bfe_u32 v1, v0, 4, 2
	v_and_b32_e32 v0, 15, v0
	v_lshlrev_b32_e32 v2, 6, v0
	v_mov_b32_e32 v3, v65
	v_lshlrev_b32_e32 v4, 3, v1
	v_mov_b32_e32 v5, v65
	v_lshl_add_u64 v[62:63], s[26:27], 0, v[2:3]
	v_lshl_add_u64 v[2:3], v[62:63], 0, v[4:5]
	s_mov_b64 s[0:1], 0x2d00000
	v_lshl_add_u64 v[148:149], v[2:3], 0, s[0:1]
	v_lshlrev_b32_e32 v150, 4, v1
	v_mov_b32_e32 v151, v65
	s_lshl_b32 s2, s5, 3
	s_mov_b32 s8, s5

.LBB0_390:
	v_mul_lo_u32 v0, v143, s46
	v_add_u32_e32 v89, s5, v0
	s_cmpk_lg_i32 s46, 0x100
	s_cbranch_scc1 .Lcmpr_orig
	s_mov_b64 s[12:13], exec
	v_readfirstlane_b32 s0, v143
	s_cmp_lg_u32 s0, 0
	s_cbranch_scc1 .LBB0_399
	s_lshr_b32 s2, s5, 7
	s_lshr_b32 s19, s5, 6
	s_and_b32 s19, s19, 1
	s_mov_b32 s18, 0x1cd00000
	s_mov_b32 s0, 0x1d100000
	s_cmp_eq_u32 s2, 0
	s_cselect_b32 s18, s18, s0
	s_lshl_b32 s0, s19, 7
	s_add_i32 s18, s18, s0
	s_add_u32 s0, s26, s18
	s_addc_u32 s1, s27, 0
	s_lshl_b32 s18, s2, 19
	s_add_i32 s18, s18, 0x2800000
	s_add_u32 s8, s26, s18
	s_addc_u32 s9, s27, 0
	s_add_u32 s10, s8, 0x10000
	s_addc_u32 s11, s9, 0
	s_add_u32 s14, s10, 0x10000
	s_addc_u32 s15, s11, 0
	s_add_u32 s16, s14, 0x10000
	s_addc_u32 s17, s15, 0
	v_and_b32_e32 v80, 15, v208
	v_bfe_u32 v86, v208, 4, 2
	s_and_b32 s18, s5, 63
	s_lshl_b32 s18, s18, 4
	v_add_u32_e32 v64, s18, v80
	v_lshlrev_b32_e32 v64, 4, v64
	v_min_u32_e32 v64, 0x3fe0, v64
	v_lshlrev_b32_e32 v64, 8, v64
	v_lshl_add_u32 v64, v86, 4, v64
	v_lshlrev_b32_e32 v78, 12, v80
	v_lshl_add_u32 v78, v86, 4, v78
	v_add_u32_e32 v79, 0x40000, v78
	v_mov_b32_e32 v0, 0
	v_mov_b32_e32 v1, 0
	v_mov_b32_e32 v2, 0
	v_mov_b32_e32 v3, 0
	v_mov_b32_e32 v4, 0
	v_mov_b32_e32 v5, 0
	v_mov_b32_e32 v6, 0
	v_mov_b32_e32 v7, 0
	v_mov_b32_e32 v8, 0
	v_mov_b32_e32 v9, 0
	v_mov_b32_e32 v10, 0
	v_mov_b32_e32 v11, 0
	v_mov_b32_e32 v12, 0
	v_mov_b32_e32 v13, 0
	v_mov_b32_e32 v14, 0
	v_mov_b32_e32 v15, 0
	v_mov_b32_e32 v16, 0
	v_mov_b32_e32 v17, 0
	v_mov_b32_e32 v18, 0
	v_mov_b32_e32 v19, 0
	v_mov_b32_e32 v20, 0
	v_mov_b32_e32 v21, 0
	v_mov_b32_e32 v22, 0
	v_mov_b32_e32 v23, 0
	v_mov_b32_e32 v24, 0
	v_mov_b32_e32 v25, 0
	v_mov_b32_e32 v26, 0
	v_mov_b32_e32 v27, 0
	v_mov_b32_e32 v28, 0
	v_mov_b32_e32 v29, 0
	v_mov_b32_e32 v30, 0
	v_mov_b32_e32 v31, 0
	global_load_dwordx4 v[32:35], v64, s[0:1]
	global_load_dwordx4 v[40:43], v78, s[8:9] offset:0
	global_load_dwordx4 v[44:47], v78, s[10:11] offset:0
	global_load_dwordx4 v[48:51], v78, s[14:15] offset:0
	global_load_dwordx4 v[52:55], v78, s[16:17] offset:0
	global_load_dwordx4 v[56:59], v79, s[8:9] offset:0
	global_load_dwordx4 v[60:63], v79, s[10:11] offset:0
	global_load_dwordx4 v[66:69], v79, s[14:15] offset:0
	global_load_dwordx4 v[70:73], v79, s[16:17] offset:0
	s_mov_b32 s18, 32
.Lcmpr_loop:
	global_load_dwordx4 v[36:39], v64, s[0:1] offset:64
	s_waitcnt vmcnt(8)
	v_mfma_f32_16x16x32_bf16 v[0:3], v[40:43], v[32:35], v[0:3]
	global_load_dwordx4 v[40:43], v78, s[8:9] offset:64
	s_waitcnt vmcnt(8)
	v_mfma_f32_16x16x32_bf16 v[4:7], v[44:47], v[32:35], v[4:7]
	global_load_dwordx4 v[44:47], v78, s[10:11] offset:64
	s_waitcnt vmcnt(8)
	v_mfma_f32_16x16x32_bf16 v[8:11], v[48:51], v[32:35], v[8:11]
	global_load_dwordx4 v[48:51], v78, s[14:15] offset:64
	s_waitcnt vmcnt(8)
	v_mfma_f32_16x16x32_bf16 v[12:15], v[52:55], v[32:35], v[12:15]
	global_load_dwordx4 v[52:55], v78, s[16:17] offset:64
	s_waitcnt vmcnt(8)
	v_mfma_f32_16x16x32_bf16 v[16:19], v[56:59], v[32:35], v[16:19]
	global_load_dwordx4 v[56:59], v79, s[8:9] offset:64
	s_waitcnt vmcnt(8)
	v_mfma_f32_16x16x32_bf16 v[20:23], v[60:63], v[32:35], v[20:23]
	global_load_dwordx4 v[60:63], v79, s[10:11] offset:64
	s_waitcnt vmcnt(8)
	v_mfma_f32_16x16x32_bf16 v[24:27], v[66:69], v[32:35], v[24:27]
	global_load_dwordx4 v[66:69], v79, s[14:15] offset:64
	s_waitcnt vmcnt(8)
	v_mfma_f32_16x16x32_bf16 v[28:31], v[70:73], v[32:35], v[28:31]
	global_load_dwordx4 v[70:73], v79, s[16:17] offset:64
	global_load_dwordx4 v[32:35], v64, s[0:1] offset:256
	s_waitcnt vmcnt(8)
	v_mfma_f32_16x16x32_bf16 v[0:3], v[40:43], v[36:39], v[0:3]
	global_load_dwordx4 v[40:43], v78, s[8:9] offset:128
	s_waitcnt vmcnt(8)
	v_mfma_f32_16x16x32_bf16 v[4:7], v[44:47], v[36:39], v[4:7]
	global_load_dwordx4 v[44:47], v78, s[10:11] offset:128
	s_waitcnt vmcnt(8)
	v_mfma_f32_16x16x32_bf16 v[8:11], v[48:51], v[36:39], v[8:11]
	global_load_dwordx4 v[48:51], v78, s[14:15] offset:128
	s_waitcnt vmcnt(8)
	v_mfma_f32_16x16x32_bf16 v[12:15], v[52:55], v[36:39], v[12:15]
	global_load_dwordx4 v[52:55], v78, s[16:17] offset:128
	s_waitcnt vmcnt(8)
	v_mfma_f32_16x16x32_bf16 v[16:19], v[56:59], v[36:39], v[16:19]
	global_load_dwordx4 v[56:59], v79, s[8:9] offset:128
	s_waitcnt vmcnt(8)
	v_mfma_f32_16x16x32_bf16 v[20:23], v[60:63], v[36:39], v[20:23]
	global_load_dwordx4 v[60:63], v79, s[10:11] offset:128
	s_waitcnt vmcnt(8)
	v_mfma_f32_16x16x32_bf16 v[24:27], v[66:69], v[36:39], v[24:27]
	global_load_dwordx4 v[66:69], v79, s[14:15] offset:128
	s_waitcnt vmcnt(8)
	v_mfma_f32_16x16x32_bf16 v[28:31], v[70:73], v[36:39], v[28:31]
	global_load_dwordx4 v[70:73], v79, s[16:17] offset:128
	s_add_u32 s0, s0, 0x100
	s_addc_u32 s1, s1, 0
	s_add_u32 s8, s8, 0x80
	s_addc_u32 s9, s9, 0
	s_add_u32 s10, s10, 0x80
	s_addc_u32 s11, s11, 0
	s_add_u32 s14, s14, 0x80
	s_addc_u32 s15, s15, 0
	s_add_u32 s16, s16, 0x80
	s_addc_u32 s17, s17, 0
	s_add_i32 s18, s18, -1
	s_cmp_lg_u32 s18, 0
	s_cbranch_scc1 .Lcmpr_loop
	s_waitcnt vmcnt(0)
	s_lshl_b32 s18, s2, 9
	s_add_u32 s0, s26, s18
	s_addc_u32 s1, s27, 0
	v_lshlrev_b32_e32 v87, 4, v86
	global_load_dwordx4 v[40:43], v87, s[0:1] offset:0
	global_load_dwordx4 v[44:47], v87, s[0:1] offset:64
	global_load_dwordx4 v[48:51], v87, s[0:1] offset:128
	global_load_dwordx4 v[52:55], v87, s[0:1] offset:192
	global_load_dwordx4 v[56:59], v87, s[0:1] offset:256
	global_load_dwordx4 v[60:63], v87, s[0:1] offset:320
	global_load_dwordx4 v[66:69], v87, s[0:1] offset:384
	global_load_dwordx4 v[70:73], v87, s[0:1] offset:448
	s_lshl_b32 s18, s2, 14
	s_add_i32 s18, s18, 0x2900000
	s_add_u32 s8, s26, s18
	s_addc_u32 s9, s27, 0
	s_add_u32 s10, s8, 0x1000
	s_addc_u32 s11, s9, 0
	s_add_u32 s14, s10, 0x1000
	s_addc_u32 s15, s11, 0
	s_add_u32 s16, s14, 0x1000
	s_addc_u32 s17, s15, 0
	v_lshlrev_b32_e32 v78, 8, v80
	v_lshl_add_u32 v78, v86, 3, v78
	s_waitcnt vmcnt(0)
	s_nop 7
	v_add_f32_e32 v0, v0, v40
	v_mul_f32_e32 v40, v0, v0
	v_mul_f32_e32 v40, v40, v0
	v_fmamk_f32 v40, v40, 0x3d372713, v0
	v_mul_f32_e32 v40, 0x40135761, v40
	v_exp_f32_e32 v40, v40
	s_nop 0
	v_add_f32_e32 v40, 1.0, v40
	v_rcp_f32_e32 v40, v40
	s_nop 0
	v_fma_f32 v40, v40, -2.0, 2.0
	v_mul_f32_e32 v0, 0.5, v0
	v_mul_f32_e32 v0, v0, v40
	v_add_f32_e32 v1, v1, v41
	v_mul_f32_e32 v41, v1, v1
	v_mul_f32_e32 v41, v41, v1
	v_fmamk_f32 v41, v41, 0x3d372713, v1
	v_mul_f32_e32 v41, 0x40135761, v41
	v_exp_f32_e32 v41, v41
	s_nop 0
	v_add_f32_e32 v41, 1.0, v41
	v_rcp_f32_e32 v41, v41
	s_nop 0
	v_fma_f32 v41, v41, -2.0, 2.0
	v_mul_f32_e32 v1, 0.5, v1
	v_mul_f32_e32 v1, v1, v41
	v_add_f32_e32 v2, v2, v42
	v_mul_f32_e32 v42, v2, v2
	v_mul_f32_e32 v42, v42, v2
	v_fmamk_f32 v42, v42, 0x3d372713, v2
	v_mul_f32_e32 v42, 0x40135761, v42
	v_exp_f32_e32 v42, v42
	s_nop 0
	v_add_f32_e32 v42, 1.0, v42
	v_rcp_f32_e32 v42, v42
	s_nop 0
	v_fma_f32 v42, v42, -2.0, 2.0
	v_mul_f32_e32 v2, 0.5, v2
	v_mul_f32_e32 v2, v2, v42
	v_add_f32_e32 v3, v3, v43
	v_mul_f32_e32 v43, v3, v3
	v_mul_f32_e32 v43, v43, v3
	v_fmamk_f32 v43, v43, 0x3d372713, v3
	v_mul_f32_e32 v43, 0x40135761, v43
	v_exp_f32_e32 v43, v43
	s_nop 0
	v_add_f32_e32 v43, 1.0, v43
	v_rcp_f32_e32 v43, v43
	s_nop 0
	v_fma_f32 v43, v43, -2.0, 2.0
	v_mul_f32_e32 v3, 0.5, v3
	v_mul_f32_e32 v3, v3, v43
	v_add_f32_e32 v4, v4, v44
	v_mul_f32_e32 v44, v4, v4
	v_mul_f32_e32 v44, v44, v4
	v_fmamk_f32 v44, v44, 0x3d372713, v4
	v_mul_f32_e32 v44, 0x40135761, v44
	v_exp_f32_e32 v44, v44
	s_nop 0
	v_add_f32_e32 v44, 1.0, v44
	v_rcp_f32_e32 v44, v44
	s_nop 0
	v_fma_f32 v44, v44, -2.0, 2.0
	v_mul_f32_e32 v4, 0.5, v4
	v_mul_f32_e32 v4, v4, v44
	v_add_f32_e32 v5, v5, v45
	v_mul_f32_e32 v45, v5, v5
	v_mul_f32_e32 v45, v45, v5
	v_fmamk_f32 v45, v45, 0x3d372713, v5
	v_mul_f32_e32 v45, 0x40135761, v45
	v_exp_f32_e32 v45, v45
	s_nop 0
	v_add_f32_e32 v45, 1.0, v45
	v_rcp_f32_e32 v45, v45
	s_nop 0
	v_fma_f32 v45, v45, -2.0, 2.0
	v_mul_f32_e32 v5, 0.5, v5
	v_mul_f32_e32 v5, v5, v45
	v_add_f32_e32 v6, v6, v46
	v_mul_f32_e32 v46, v6, v6
	v_mul_f32_e32 v46, v46, v6
	v_fmamk_f32 v46, v46, 0x3d372713, v6
	v_mul_f32_e32 v46, 0x40135761, v46
	v_exp_f32_e32 v46, v46
	s_nop 0
	v_add_f32_e32 v46, 1.0, v46
	v_rcp_f32_e32 v46, v46
	s_nop 0
	v_fma_f32 v46, v46, -2.0, 2.0
	v_mul_f32_e32 v6, 0.5, v6
	v_mul_f32_e32 v6, v6, v46
	v_add_f32_e32 v7, v7, v47
	v_mul_f32_e32 v47, v7, v7
	v_mul_f32_e32 v47, v47, v7
	v_fmamk_f32 v47, v47, 0x3d372713, v7
	v_mul_f32_e32 v47, 0x40135761, v47
	v_exp_f32_e32 v47, v47
	s_nop 0
	v_add_f32_e32 v47, 1.0, v47
	v_rcp_f32_e32 v47, v47
	s_nop 0
	v_fma_f32 v47, v47, -2.0, 2.0
	v_mul_f32_e32 v7, 0.5, v7
	v_mul_f32_e32 v7, v7, v47
	v_add_f32_e32 v8, v8, v48
	v_mul_f32_e32 v48, v8, v8
	v_mul_f32_e32 v48, v48, v8
	v_fmamk_f32 v48, v48, 0x3d372713, v8
	v_mul_f32_e32 v48, 0x40135761, v48
	v_exp_f32_e32 v48, v48
	s_nop 0
	v_add_f32_e32 v48, 1.0, v48
	v_rcp_f32_e32 v48, v48
	s_nop 0
	v_fma_f32 v48, v48, -2.0, 2.0
	v_mul_f32_e32 v8, 0.5, v8
	v_mul_f32_e32 v8, v8, v48
	v_add_f32_e32 v9, v9, v49
	v_mul_f32_e32 v49, v9, v9
	v_mul_f32_e32 v49, v49, v9
	v_fmamk_f32 v49, v49, 0x3d372713, v9
	v_mul_f32_e32 v49, 0x40135761, v49
	v_exp_f32_e32 v49, v49
	s_nop 0
	v_add_f32_e32 v49, 1.0, v49
	v_rcp_f32_e32 v49, v49
	s_nop 0
	v_fma_f32 v49, v49, -2.0, 2.0
	v_mul_f32_e32 v9, 0.5, v9
	v_mul_f32_e32 v9, v9, v49
	v_add_f32_e32 v10, v10, v50
	v_mul_f32_e32 v50, v10, v10
	v_mul_f32_e32 v50, v50, v10
	v_fmamk_f32 v50, v50, 0x3d372713, v10
	v_mul_f32_e32 v50, 0x40135761, v50
	v_exp_f32_e32 v50, v50
	s_nop 0
	v_add_f32_e32 v50, 1.0, v50
	v_rcp_f32_e32 v50, v50
	s_nop 0
	v_fma_f32 v50, v50, -2.0, 2.0
	v_mul_f32_e32 v10, 0.5, v10
	v_mul_f32_e32 v10, v10, v50
	v_add_f32_e32 v11, v11, v51
	v_mul_f32_e32 v51, v11, v11
	v_mul_f32_e32 v51, v51, v11
	v_fmamk_f32 v51, v51, 0x3d372713, v11
	v_mul_f32_e32 v51, 0x40135761, v51
	v_exp_f32_e32 v51, v51
	s_nop 0
	v_add_f32_e32 v51, 1.0, v51
	v_rcp_f32_e32 v51, v51
	s_nop 0
	v_fma_f32 v51, v51, -2.0, 2.0
	v_mul_f32_e32 v11, 0.5, v11
	v_mul_f32_e32 v11, v11, v51
	v_add_f32_e32 v12, v12, v52
	v_mul_f32_e32 v52, v12, v12
	v_mul_f32_e32 v52, v52, v12
	v_fmamk_f32 v52, v52, 0x3d372713, v12
	v_mul_f32_e32 v52, 0x40135761, v52
	v_exp_f32_e32 v52, v52
	s_nop 0
	v_add_f32_e32 v52, 1.0, v52
	v_rcp_f32_e32 v52, v52
	s_nop 0
	v_fma_f32 v52, v52, -2.0, 2.0
	v_mul_f32_e32 v12, 0.5, v12
	v_mul_f32_e32 v12, v12, v52
	v_add_f32_e32 v13, v13, v53
	v_mul_f32_e32 v53, v13, v13
	v_mul_f32_e32 v53, v53, v13
	v_fmamk_f32 v53, v53, 0x3d372713, v13
	v_mul_f32_e32 v53, 0x40135761, v53
	v_exp_f32_e32 v53, v53
	s_nop 0
	v_add_f32_e32 v53, 1.0, v53
	v_rcp_f32_e32 v53, v53
	s_nop 0
	v_fma_f32 v53, v53, -2.0, 2.0
	v_mul_f32_e32 v13, 0.5, v13
	v_mul_f32_e32 v13, v13, v53
	v_add_f32_e32 v14, v14, v54
	v_mul_f32_e32 v54, v14, v14
	v_mul_f32_e32 v54, v54, v14
	v_fmamk_f32 v54, v54, 0x3d372713, v14
	v_mul_f32_e32 v54, 0x40135761, v54
	v_exp_f32_e32 v54, v54
	s_nop 0
	v_add_f32_e32 v54, 1.0, v54
	v_rcp_f32_e32 v54, v54
	s_nop 0
	v_fma_f32 v54, v54, -2.0, 2.0
	v_mul_f32_e32 v14, 0.5, v14
	v_mul_f32_e32 v14, v14, v54
	v_add_f32_e32 v15, v15, v55
	v_mul_f32_e32 v55, v15, v15
	v_mul_f32_e32 v55, v55, v15
	v_fmamk_f32 v55, v55, 0x3d372713, v15
	v_mul_f32_e32 v55, 0x40135761, v55
	v_exp_f32_e32 v55, v55
	s_nop 0
	v_add_f32_e32 v55, 1.0, v55
	v_rcp_f32_e32 v55, v55
	s_nop 0
	v_fma_f32 v55, v55, -2.0, 2.0
	v_mul_f32_e32 v15, 0.5, v15
	v_mul_f32_e32 v15, v15, v55
	v_add_f32_e32 v16, v16, v56
	v_mul_f32_e32 v56, v16, v16
	v_mul_f32_e32 v56, v56, v16
	v_fmamk_f32 v56, v56, 0x3d372713, v16
	v_mul_f32_e32 v56, 0x40135761, v56
	v_exp_f32_e32 v56, v56
	s_nop 0
	v_add_f32_e32 v56, 1.0, v56
	v_rcp_f32_e32 v56, v56
	s_nop 0
	v_fma_f32 v56, v56, -2.0, 2.0
	v_mul_f32_e32 v16, 0.5, v16
	v_mul_f32_e32 v16, v16, v56
	v_add_f32_e32 v17, v17, v57
	v_mul_f32_e32 v57, v17, v17
	v_mul_f32_e32 v57, v57, v17
	v_fmamk_f32 v57, v57, 0x3d372713, v17
	v_mul_f32_e32 v57, 0x40135761, v57
	v_exp_f32_e32 v57, v57
	s_nop 0
	v_add_f32_e32 v57, 1.0, v57
	v_rcp_f32_e32 v57, v57
	s_nop 0
	v_fma_f32 v57, v57, -2.0, 2.0
	v_mul_f32_e32 v17, 0.5, v17
	v_mul_f32_e32 v17, v17, v57
	v_add_f32_e32 v18, v18, v58
	v_mul_f32_e32 v58, v18, v18
	v_mul_f32_e32 v58, v58, v18
	v_fmamk_f32 v58, v58, 0x3d372713, v18
	v_mul_f32_e32 v58, 0x40135761, v58
	v_exp_f32_e32 v58, v58
	s_nop 0
	v_add_f32_e32 v58, 1.0, v58
	v_rcp_f32_e32 v58, v58
	s_nop 0
	v_fma_f32 v58, v58, -2.0, 2.0
	v_mul_f32_e32 v18, 0.5, v18
	v_mul_f32_e32 v18, v18, v58
	v_add_f32_e32 v19, v19, v59
	v_mul_f32_e32 v59, v19, v19
	v_mul_f32_e32 v59, v59, v19
	v_fmamk_f32 v59, v59, 0x3d372713, v19
	v_mul_f32_e32 v59, 0x40135761, v59
	v_exp_f32_e32 v59, v59
	s_nop 0
	v_add_f32_e32 v59, 1.0, v59
	v_rcp_f32_e32 v59, v59
	s_nop 0
	v_fma_f32 v59, v59, -2.0, 2.0
	v_mul_f32_e32 v19, 0.5, v19
	v_mul_f32_e32 v19, v19, v59
	v_add_f32_e32 v20, v20, v60
	v_mul_f32_e32 v60, v20, v20
	v_mul_f32_e32 v60, v60, v20
	v_fmamk_f32 v60, v60, 0x3d372713, v20
	v_mul_f32_e32 v60, 0x40135761, v60
	v_exp_f32_e32 v60, v60
	s_nop 0
	v_add_f32_e32 v60, 1.0, v60
	v_rcp_f32_e32 v60, v60
	s_nop 0
	v_fma_f32 v60, v60, -2.0, 2.0
	v_mul_f32_e32 v20, 0.5, v20
	v_mul_f32_e32 v20, v20, v60
	v_add_f32_e32 v21, v21, v61
	v_mul_f32_e32 v61, v21, v21
	v_mul_f32_e32 v61, v61, v21
	v_fmamk_f32 v61, v61, 0x3d372713, v21
	v_mul_f32_e32 v61, 0x40135761, v61
	v_exp_f32_e32 v61, v61
	s_nop 0
	v_add_f32_e32 v61, 1.0, v61
	v_rcp_f32_e32 v61, v61
	s_nop 0
	v_fma_f32 v61, v61, -2.0, 2.0
	v_mul_f32_e32 v21, 0.5, v21
	v_mul_f32_e32 v21, v21, v61
	v_add_f32_e32 v22, v22, v62
	v_mul_f32_e32 v62, v22, v22
	v_mul_f32_e32 v62, v62, v22
	v_fmamk_f32 v62, v62, 0x3d372713, v22
	v_mul_f32_e32 v62, 0x40135761, v62
	v_exp_f32_e32 v62, v62
	s_nop 0
	v_add_f32_e32 v62, 1.0, v62
	v_rcp_f32_e32 v62, v62
	s_nop 0
	v_fma_f32 v62, v62, -2.0, 2.0
	v_mul_f32_e32 v22, 0.5, v22
	v_mul_f32_e32 v22, v22, v62
	v_add_f32_e32 v23, v23, v63
	v_mul_f32_e32 v63, v23, v23
	v_mul_f32_e32 v63, v63, v23
	v_fmamk_f32 v63, v63, 0x3d372713, v23
	v_mul_f32_e32 v63, 0x40135761, v63
	v_exp_f32_e32 v63, v63
	s_nop 0
	v_add_f32_e32 v63, 1.0, v63
	v_rcp_f32_e32 v63, v63
	s_nop 0
	v_fma_f32 v63, v63, -2.0, 2.0
	v_mul_f32_e32 v23, 0.5, v23
	v_mul_f32_e32 v23, v23, v63
	v_add_f32_e32 v24, v24, v66
	v_mul_f32_e32 v66, v24, v24
	v_mul_f32_e32 v66, v66, v24
	v_fmamk_f32 v66, v66, 0x3d372713, v24
	v_mul_f32_e32 v66, 0x40135761, v66
	v_exp_f32_e32 v66, v66
	s_nop 0
	v_add_f32_e32 v66, 1.0, v66
	v_rcp_f32_e32 v66, v66
	s_nop 0
	v_fma_f32 v66, v66, -2.0, 2.0
	v_mul_f32_e32 v24, 0.5, v24
	v_mul_f32_e32 v24, v24, v66
	v_add_f32_e32 v25, v25, v67
	v_mul_f32_e32 v67, v25, v25
	v_mul_f32_e32 v67, v67, v25
	v_fmamk_f32 v67, v67, 0x3d372713, v25
	v_mul_f32_e32 v67, 0x40135761, v67
	v_exp_f32_e32 v67, v67
	s_nop 0
	v_add_f32_e32 v67, 1.0, v67
	v_rcp_f32_e32 v67, v67
	s_nop 0
	v_fma_f32 v67, v67, -2.0, 2.0
	v_mul_f32_e32 v25, 0.5, v25
	v_mul_f32_e32 v25, v25, v67
	v_add_f32_e32 v26, v26, v68
	v_mul_f32_e32 v68, v26, v26
	v_mul_f32_e32 v68, v68, v26
	v_fmamk_f32 v68, v68, 0x3d372713, v26
	v_mul_f32_e32 v68, 0x40135761, v68
	v_exp_f32_e32 v68, v68
	s_nop 0
	v_add_f32_e32 v68, 1.0, v68
	v_rcp_f32_e32 v68, v68
	s_nop 0
	v_fma_f32 v68, v68, -2.0, 2.0
	v_mul_f32_e32 v26, 0.5, v26
	v_mul_f32_e32 v26, v26, v68
	v_add_f32_e32 v27, v27, v69
	v_mul_f32_e32 v69, v27, v27
	v_mul_f32_e32 v69, v69, v27
	v_fmamk_f32 v69, v69, 0x3d372713, v27
	v_mul_f32_e32 v69, 0x40135761, v69
	v_exp_f32_e32 v69, v69
	s_nop 0
	v_add_f32_e32 v69, 1.0, v69
	v_rcp_f32_e32 v69, v69
	s_nop 0
	v_fma_f32 v69, v69, -2.0, 2.0
	v_mul_f32_e32 v27, 0.5, v27
	v_mul_f32_e32 v27, v27, v69
	v_add_f32_e32 v28, v28, v70
	v_mul_f32_e32 v70, v28, v28
	v_mul_f32_e32 v70, v70, v28
	v_fmamk_f32 v70, v70, 0x3d372713, v28
	v_mul_f32_e32 v70, 0x40135761, v70
	v_exp_f32_e32 v70, v70
	s_nop 0
	v_add_f32_e32 v70, 1.0, v70
	v_rcp_f32_e32 v70, v70
	s_nop 0
	v_fma_f32 v70, v70, -2.0, 2.0
	v_mul_f32_e32 v28, 0.5, v28
	v_mul_f32_e32 v28, v28, v70
	v_add_f32_e32 v29, v29, v71
	v_mul_f32_e32 v71, v29, v29
	v_mul_f32_e32 v71, v71, v29
	v_fmamk_f32 v71, v71, 0x3d372713, v29
	v_mul_f32_e32 v71, 0x40135761, v71
	v_exp_f32_e32 v71, v71
	s_nop 0
	v_add_f32_e32 v71, 1.0, v71
	v_rcp_f32_e32 v71, v71
	s_nop 0
	v_fma_f32 v71, v71, -2.0, 2.0
	v_mul_f32_e32 v29, 0.5, v29
	v_mul_f32_e32 v29, v29, v71
	v_add_f32_e32 v30, v30, v72
	v_mul_f32_e32 v72, v30, v30
	v_mul_f32_e32 v72, v72, v30
	v_fmamk_f32 v72, v72, 0x3d372713, v30
	v_mul_f32_e32 v72, 0x40135761, v72
	v_exp_f32_e32 v72, v72
	s_nop 0
	v_add_f32_e32 v72, 1.0, v72
	v_rcp_f32_e32 v72, v72
	s_nop 0
	v_fma_f32 v72, v72, -2.0, 2.0
	v_mul_f32_e32 v30, 0.5, v30
	v_mul_f32_e32 v30, v30, v72
	v_add_f32_e32 v31, v31, v73
	v_mul_f32_e32 v73, v31, v31
	v_mul_f32_e32 v73, v73, v31
	v_fmamk_f32 v73, v73, 0x3d372713, v31
	v_mul_f32_e32 v73, 0x40135761, v73
	v_exp_f32_e32 v73, v73
	s_nop 0
	v_add_f32_e32 v73, 1.0, v73
	v_rcp_f32_e32 v73, v73
	s_nop 0
	v_fma_f32 v73, v73, -2.0, 2.0
	v_mul_f32_e32 v31, 0.5, v31
	v_mul_f32_e32 v31, v31, v73
	v_cvt_pk_bf16_f32 v0, v0, v1
	v_cvt_pk_bf16_f32 v1, v2, v3
	v_cvt_pk_bf16_f32 v2, v4, v5
	v_cvt_pk_bf16_f32 v3, v6, v7
	v_cvt_pk_bf16_f32 v8, v8, v9
	v_cvt_pk_bf16_f32 v9, v10, v11
	v_cvt_pk_bf16_f32 v10, v12, v13
	v_cvt_pk_bf16_f32 v11, v14, v15
	v_cvt_pk_bf16_f32 v16, v16, v17
	v_cvt_pk_bf16_f32 v17, v18, v19
	v_cvt_pk_bf16_f32 v18, v20, v21
	v_cvt_pk_bf16_f32 v19, v22, v23
	v_cvt_pk_bf16_f32 v24, v24, v25
	v_cvt_pk_bf16_f32 v25, v26, v27
	v_cvt_pk_bf16_f32 v26, v28, v29
	v_cvt_pk_bf16_f32 v27, v30, v31
	v_mov_b32_e32 v4, 0
	v_mov_b32_e32 v5, 0
	v_mov_b32_e32 v6, 0
	v_mov_b32_e32 v7, 0
	v_mov_b32_e32 v12, 0
	v_mov_b32_e32 v13, 0
	v_mov_b32_e32 v14, 0
	v_mov_b32_e32 v15, 0
	v_mov_b32_e32 v20, 0
	v_mov_b32_e32 v21, 0
	v_mov_b32_e32 v22, 0
	v_mov_b32_e32 v23, 0
	v_mov_b32_e32 v28, 0
	v_mov_b32_e32 v29, 0
	v_mov_b32_e32 v30, 0
	v_mov_b32_e32 v31, 0
	global_load_dwordx2 v[40:41], v78, s[8:9] offset:0
	global_load_dwordx2 v[42:43], v78, s[8:9] offset:32
	global_load_dwordx2 v[44:45], v78, s[10:11] offset:0
	global_load_dwordx2 v[46:47], v78, s[10:11] offset:32
	global_load_dwordx2 v[48:49], v78, s[14:15] offset:0
	global_load_dwordx2 v[50:51], v78, s[14:15] offset:32
	global_load_dwordx2 v[52:53], v78, s[16:17] offset:0
	global_load_dwordx2 v[54:55], v78, s[16:17] offset:32
	global_load_dwordx2 v[56:57], v78, s[8:9] offset:64
	global_load_dwordx2 v[58:59], v78, s[8:9] offset:96
	global_load_dwordx2 v[60:61], v78, s[10:11] offset:64
	global_load_dwordx2 v[62:63], v78, s[10:11] offset:96
	global_load_dwordx2 v[66:67], v78, s[14:15] offset:64
	global_load_dwordx2 v[68:69], v78, s[14:15] offset:96
	global_load_dwordx2 v[70:71], v78, s[16:17] offset:64
	global_load_dwordx2 v[72:73], v78, s[16:17] offset:96
	s_waitcnt vmcnt(0)
	v_mfma_f32_16x16x32_bf16 v[4:7], v[40:43], v[0:3], v[4:7]
	v_mfma_f32_16x16x32_bf16 v[12:15], v[44:47], v[0:3], v[12:15]
	v_mfma_f32_16x16x32_bf16 v[20:23], v[48:51], v[0:3], v[20:23]
	v_mfma_f32_16x16x32_bf16 v[28:31], v[52:55], v[0:3], v[28:31]
	v_mfma_f32_16x16x32_bf16 v[4:7], v[56:59], v[8:11], v[4:7]
	v_mfma_f32_16x16x32_bf16 v[12:15], v[60:63], v[8:11], v[12:15]
	v_mfma_f32_16x16x32_bf16 v[20:23], v[66:69], v[8:11], v[20:23]
	v_mfma_f32_16x16x32_bf16 v[28:31], v[70:73], v[8:11], v[28:31]
	global_load_dwordx2 v[40:41], v78, s[8:9] offset:128
	global_load_dwordx2 v[42:43], v78, s[8:9] offset:160
	global_load_dwordx2 v[44:45], v78, s[10:11] offset:128
	global_load_dwordx2 v[46:47], v78, s[10:11] offset:160
	global_load_dwordx2 v[48:49], v78, s[14:15] offset:128
	global_load_dwordx2 v[50:51], v78, s[14:15] offset:160
	global_load_dwordx2 v[52:53], v78, s[16:17] offset:128
	global_load_dwordx2 v[54:55], v78, s[16:17] offset:160
	global_load_dwordx2 v[56:57], v78, s[8:9] offset:192
	global_load_dwordx2 v[58:59], v78, s[8:9] offset:224
	global_load_dwordx2 v[60:61], v78, s[10:11] offset:192
	global_load_dwordx2 v[62:63], v78, s[10:11] offset:224
	global_load_dwordx2 v[66:67], v78, s[14:15] offset:192
	global_load_dwordx2 v[68:69], v78, s[14:15] offset:224
	global_load_dwordx2 v[70:71], v78, s[16:17] offset:192
	global_load_dwordx2 v[72:73], v78, s[16:17] offset:224
	s_waitcnt vmcnt(0)
	v_mfma_f32_16x16x32_bf16 v[4:7], v[40:43], v[16:19], v[4:7]
	v_mfma_f32_16x16x32_bf16 v[12:15], v[44:47], v[16:19], v[12:15]
	v_mfma_f32_16x16x32_bf16 v[20:23], v[48:51], v[16:19], v[20:23]
	v_mfma_f32_16x16x32_bf16 v[28:31], v[52:55], v[16:19], v[28:31]
	v_mfma_f32_16x16x32_bf16 v[4:7], v[56:59], v[24:27], v[4:7]
	v_mfma_f32_16x16x32_bf16 v[12:15], v[60:63], v[24:27], v[12:15]
	v_mfma_f32_16x16x32_bf16 v[20:23], v[66:69], v[24:27], v[20:23]
	v_mfma_f32_16x16x32_bf16 v[28:31], v[70:73], v[24:27], v[28:31]
	s_nop 7
	s_nop 1
	s_and_b32 s18, s5, 63
	s_cmp_eq_u32 s2, 0
	s_cbranch_scc0 .Lcmpr_vstore
	s_lshl_b32 s0, s19, 17
	s_lshl_b32 s18, s18, 11
	s_add_i32 s0, s0, s18
	s_add_i32 s0, s0, 0x1e700000
	s_add_u32 s0, s26, s0
	s_addc_u32 s1, s27, 0
	v_lshlrev_b32_e32 v87, 6, v80
	v_lshl_add_u32 v87, v86, 3, v87
	v_cvt_pk_bf16_f32 v4, v4, v5
	v_cvt_pk_bf16_f32 v5, v6, v7
	global_store_dwordx2 v87, v[4:5], s[0:1] offset:0
	v_cvt_pk_bf16_f32 v12, v12, v13
	v_cvt_pk_bf16_f32 v13, v14, v15
	global_store_dwordx2 v87, v[12:13], s[0:1] offset:32
	v_cvt_pk_bf16_f32 v20, v20, v21
	v_cvt_pk_bf16_f32 v21, v22, v23
	global_store_dwordx2 v87, v[20:21], s[0:1] offset:1024
	v_cvt_pk_bf16_f32 v28, v28, v29
	v_cvt_pk_bf16_f32 v29, v30, v31
	global_store_dwordx2 v87, v[28:29], s[0:1] offset:1056
	s_branch .LBB0_399

.LBB0_399:
	s_or_b64 exec, exec, s[12:13]
	v_mov_b32_e32 v2, v208
	s_add_u32 s30, s26, 0x6d00000
	s_addc_u32 s31, s27, 0
	v_and_b32_e32 v102, 15, v2
	v_lshlrev_b32_e32 v84, 6, v102
	v_mov_b32_e32 v85, v65
	s_add_u32 s34, s26, 0x1ad00000
	v_lshl_add_u64 v[0:1], s[26:27], 0, v[84:85]
	v_and_b32_e32 v86, 48, v2
	v_mov_b32_e32 v87, v65
	v_and_b32_e32 v3, 63, v2
	s_addc_u32 s35, s27, 0
	v_lshl_add_u64 v[0:1], v[0:1], 0, v[86:87]
	s_mov_b64 s[0:1], 0x1dd00000
	v_readlane_b32 s2, v254, 9
	v_bfe_u32 v4, v2, 4, 2
	v_lshl_add_u64 v[82:83], v[0:1], 0, s[0:1]
	v_lshlrev_b32_e32 v0, 2, v3
	s_add_u32 s36, s26, 0x1e500004
	v_readlane_b32 s3, v254, 10
	v_lshlrev_b32_e32 v103, 3, v4
	v_lshlrev_b32_e32 v88, 2, v4
	v_xor_b32_e32 v100, 64, v0
	v_xor_b32_e32 v101, 0x80, v0
	s_addc_u32 s37, s27, 0
	s_mov_b64 s[0:1], -1
	s_and_b64 vcc, exec, s[2:3]
	s_cbranch_vccnz .Lwin_generic
	v_readfirstlane_b32 s1, v143
	v_mov_b32_e32 v53, v102
	v_mov_b32_e32 v54, v88
	v_mov_b32_e32 v55, v103
	v_mov_b32_e32 v64, v100
	v_mov_b32_e32 v66, v101
	s_lshr_b32 s21, s5, 3
	s_and_b32 s21, s21, 1
	s_lshl_b32 s20, s21, 3
	s_add_i32 s20, s20, s1
	s_lshl_b32 s39, s20, 7
	s_mul_i32 s56, s20, 6
	s_and_b32 s7, s5, 7
	s_lshl_b32 s7, s7, 7
	s_lshr_b32 s0, s5, 4
	s_and_b32 s0, s0, 15
	s_lshl_b32 s0, s0, 3
	s_add_i32 s7, s7, s0
	s_lshl_b32 s0, s21, 21
	s_add_i32 s2, s0, 0x1dd00000
	s_add_u32 s12, s26, s2
	s_addc_u32 s13, s27, 0
	s_add_i32 s2, s0, 0x1e100000
	s_add_u32 s14, s26, s2
	s_addc_u32 s15, s27, 0
	v_lshlrev_b32_e32 v51, 6, v53
	v_lshl_add_u32 v51, v55, 1, v51
	s_mov_b32 s40, 0x3e38aa3b
	s_mov_b32 s41, 0x3e38aa3b
	s_mov_b32 s57, 0x20400
	s_lshl_b32 s28, s1, 12
	v_and_b32_e32 v40, 63, v208
	v_add_u32_e32 v40, 0xffffffe0, v40
	v_lshlrev_b32_e32 v47, 2, v40
	v_add_u32_e32 v47, 0x80, v47
	v_add_u32_e32 v47, s28, v47
	v_mov_b32_e32 v46, 0xf149f2ca
	s_mov_b32 s0, 10
.Lw_lut:
	v_max_i32_e32 v41, 0, v40
	v_min_i32_e32 v41, 0x3ff, v41
	v_cvt_f32_u32_e32 v42, v41
	v_mul_f32_e32 v42, 0x3d800000, v42
	v_log_f32_e32 v42, v42
	s_nop 0
	v_mul_f32_e32 v42, 0x40124925, v42
	v_cvt_i32_f32_e32 v42, v42
	v_med3_i32 v42, v42, 0, 15
	v_add_u32_e32 v42, 16, v42
	v_cmp_gt_u32_e32 vcc, 16, v41
	s_nop 1
	v_cndmask_b32_e32 v42, v42, v41, vcc
	v_lshl_add_u32 v42, v42, 4, s20
	v_lshl_add_u32 v42, v42, 2, s57
	ds_read_b32 v42, v42
	v_cmp_gt_u32_e32 vcc, 0x200, v40
	s_waitcnt lgkmcnt(0)
	v_mul_f32_e32 v42, 0x3fb8aa3b, v42
	v_cndmask_b32_e32 v42, v46, v42, vcc
	ds_write_b32 v47, v42
	v_add_u32_e32 v40, 64, v40
	v_add_u32_e32 v47, 0x100, v47
	s_add_i32 s0, s0, -1
	s_cmp_lg_u32 s0, 0
	s_cbranch_scc1 .Lw_lut
	s_waitcnt lgkmcnt(0)
	s_mov_b32 s6, 0
	s_lshl_b32 s8, s7, 4
	s_add_i32 s0, s8, 0xfffffe01
	s_max_i32 s0, s0, 0
	s_lshr_b32 s0, s0, 4
	s_and_b32 s11, s0, -2
	s_sub_i32 s0, s7, s11
	s_lshr_b32 s0, s0, 1
	s_add_i32 s9, s0, 1
	s_mov_b32 s10, 0
	s_mov_b32 s3, s7
	s_mov_b32 s29, s9
	s_mov_b32 s21, 0
	s_mov_b32 s38, 0
	s_lshl_b32 s0, s8, 11
	s_add_u32 s62, s34, s0
	s_addc_u32 s63, s35, 0
	v_lshlrev_b32_e32 v40, 11, v53
	v_lshl_add_u32 v40, v55, 1, v40
	v_add_u32_e32 v40, s39, v40
	global_load_dwordx4 v[16:19], v40, s[62:63]
	global_load_dwordx4 v[20:23], v40, s[62:63] offset:64
	s_lshl_b32 s0, s11, 4
	s_sub_i32 s0, s8, s0
	s_add_i32 s0, s0, 13
	s_lshl_b32 s0, s0, 2
	s_add_i32 s0, s0, s28
	v_sub_u32_e32 v50, v53, v54
	v_lshl_add_u32 v50, v50, 2, s0
	v_readfirstlane_b32 s1, v143
	s_and_b32 s0, s1, 3
	s_lshl_b32 s0, s0, 10
	s_cmp_lt_u32 s1, 4
	s_cselect_b32 s2, s12, s14
	s_cselect_b32 s16, s13, s15
	s_add_u32 s12, s2, s0
	s_addc_u32 s13, s16, 0
	s_lshl_b32 s23, s1, 10
	s_add_i32 s23, s23, 0x8000
	v_and_b32_e32 v96, 63, v208
	v_lshlrev_b32_e32 v96, 4, v96
	v_add_u32_e32 v97, 0x8000, v96
	s_mov_b32 s18, 0
	s_mov_b32 s2, 0
	s_lshl_b32 s0, s2, 13
	s_add_i32 m0, s0, s23
	s_lshl_b32 s0, s11, 11
	s_add_u32 s16, s12, s0
	s_addc_u32 s17, s13, 0
	global_load_lds_dwordx4 v96, s[16:17]
	s_add_i32 s0, s21, 1
	s_cmp_lt_i32 s0, s29
	s_cbranch_scc1 .Lw_pfsamee1
	s_cmp_ge_i32 s38, 7
	s_cbranch_scc1 .Lw_pfgoe1
	s_add_i32 s38, s38, 1
	s_add_i32 s3, s3, 1
	s_lshl_b32 s1, s3, 4
	s_add_i32 s0, s1, 0xfffffe01
	s_max_i32 s0, s0, 0
	s_lshr_b32 s0, s0, 4
	s_and_b32 s11, s0, -2
	s_sub_i32 s0, s3, s11
	s_lshr_b32 s0, s0, 1
	s_add_i32 s29, s0, 1
	s_mov_b32 s21, 0
	s_branch .Lw_pfgoe1
.Lw_pfsamee1:
	s_mov_b32 s21, s0
	s_add_i32 s11, s11, 2
.Lw_pfgoe1:
	s_mov_b32 s2, 1
	s_lshl_b32 s0, s2, 13
	s_add_i32 m0, s0, s23
	s_lshl_b32 s0, s11, 11
	s_add_u32 s16, s12, s0
	s_addc_u32 s17, s13, 0
	global_load_lds_dwordx4 v96, s[16:17]
	s_add_i32 s0, s21, 1
	s_cmp_lt_i32 s0, s29
	s_cbranch_scc1 .Lw_pfsamee2
	s_cmp_ge_i32 s38, 7
	s_cbranch_scc1 .Lw_pfgoe2
	s_add_i32 s38, s38, 1
	s_add_i32 s3, s3, 1
	s_lshl_b32 s1, s3, 4
	s_add_i32 s0, s1, 0xfffffe01
	s_max_i32 s0, s0, 0
	s_lshr_b32 s0, s0, 4
	s_and_b32 s11, s0, -2
	s_sub_i32 s0, s3, s11
	s_lshr_b32 s0, s0, 1
	s_add_i32 s29, s0, 1
	s_mov_b32 s21, 0
	s_branch .Lw_pfgoe2

.Lw_pfgoe2:
	s_mov_b32 s2, 2
	s_lshl_b32 s0, s2, 13
	s_add_i32 m0, s0, s23
	s_lshl_b32 s0, s11, 11
	s_add_u32 s16, s12, s0
	s_addc_u32 s17, s13, 0
	global_load_lds_dwordx4 v96, s[16:17]
	s_add_i32 s0, s21, 1
	s_cmp_lt_i32 s0, s29
	s_cbranch_scc1 .Lw_pfsamee3
	s_cmp_ge_i32 s38, 7
	s_cbranch_scc1 .Lw_pfgoe3
	s_add_i32 s38, s38, 1
	s_add_i32 s3, s3, 1
	s_lshl_b32 s1, s3, 4
	s_add_i32 s0, s1, 0xfffffe01
	s_max_i32 s0, s0, 0
	s_lshr_b32 s0, s0, 4
	s_and_b32 s11, s0, -2
	s_sub_i32 s0, s3, s11
	s_lshr_b32 s0, s0, 1
	s_add_i32 s29, s0, 1
	s_mov_b32 s21, 0
	s_branch .Lw_pfgoe3

.Lw_pfgoe3:
	s_mov_b32 s2, 3
	s_lshl_b32 s0, s2, 13
	s_add_i32 m0, s0, s23
	s_lshl_b32 s0, s11, 11
	s_add_u32 s16, s12, s0
	s_addc_u32 s17, s13, 0
	global_load_lds_dwordx4 v96, s[16:17]
	s_add_i32 s0, s21, 1
	s_cmp_lt_i32 s0, s29
	s_cbranch_scc1 .Lw_pfsamee4
	s_cmp_ge_i32 s38, 7
	s_cbranch_scc1 .Lw_pfgoe4
	s_add_i32 s38, s38, 1
	s_add_i32 s3, s3, 1
	s_lshl_b32 s1, s3, 4
	s_add_i32 s0, s1, 0xfffffe01
	s_max_i32 s0, s0, 0
	s_lshr_b32 s0, s0, 4
	s_and_b32 s11, s0, -2
	s_sub_i32 s0, s3, s11
	s_lshr_b32 s0, s0, 1
	s_add_i32 s29, s0, 1
	s_mov_b32 s21, 0
	s_branch .Lw_pfgoe4

.Lw_pfgoe4:
	s_mov_b32 s2, 4
	s_lshl_b32 s0, s2, 13
	s_add_i32 m0, s0, s23
	s_lshl_b32 s0, s11, 11
	s_add_u32 s16, s12, s0
	s_addc_u32 s17, s13, 0
	global_load_lds_dwordx4 v96, s[16:17]
	s_add_i32 s0, s21, 1
	s_cmp_lt_i32 s0, s29
	s_cbranch_scc1 .Lw_pfsamee5
	s_cmp_ge_i32 s38, 7
	s_cbranch_scc1 .Lw_pfgoe5
	s_add_i32 s38, s38, 1
	s_add_i32 s3, s3, 1
	s_lshl_b32 s1, s3, 4
	s_add_i32 s0, s1, 0xfffffe01
	s_max_i32 s0, s0, 0
	s_lshr_b32 s0, s0, 4
	s_and_b32 s11, s0, -2
	s_sub_i32 s0, s3, s11
	s_lshr_b32 s0, s0, 1
	s_add_i32 s29, s0, 1
	s_mov_b32 s21, 0
	s_branch .Lw_pfgoe5

.Lw_pfgoe5:
	s_mov_b32 s2, 5
	s_lshl_b32 s0, s2, 13
	s_add_i32 m0, s0, s23
	s_lshl_b32 s0, s11, 11
	s_add_u32 s16, s12, s0
	s_addc_u32 s17, s13, 0
	global_load_lds_dwordx4 v96, s[16:17]
	s_add_i32 s0, s21, 1
	s_cmp_lt_i32 s0, s29
	s_cbranch_scc1 .Lw_pfsamee6
	s_cmp_ge_i32 s38, 7
	s_cbranch_scc1 .Lw_pfgoe6
	s_add_i32 s38, s38, 1
	s_add_i32 s3, s3, 1
	s_lshl_b32 s1, s3, 4
	s_add_i32 s0, s1, 0xfffffe01
	s_max_i32 s0, s0, 0
	s_lshr_b32 s0, s0, 4
	s_and_b32 s11, s0, -2
	s_sub_i32 s0, s3, s11
	s_lshr_b32 s0, s0, 1
	s_add_i32 s29, s0, 1
	s_mov_b32 s21, 0
	s_branch .Lw_pfgoe6

.Lw_pfgoe6:
	s_mov_b32 s2, 6
	s_lshl_b32 s0, s2, 13
	s_add_i32 m0, s0, s23
	s_lshl_b32 s0, s11, 11
	s_add_u32 s16, s12, s0
	s_addc_u32 s17, s13, 0
	global_load_lds_dwordx4 v96, s[16:17]
	v_mov_b32_e32 v48, 0xefa18f08
	v_mov_b32_e32 v49, 0
	v_mov_b32_e32 v0, 0
	v_mov_b32_e32 v1, 0
	v_mov_b32_e32 v2, 0
	v_mov_b32_e32 v3, 0
	v_mov_b32_e32 v4, 0
	v_mov_b32_e32 v5, 0
	v_mov_b32_e32 v6, 0
	v_mov_b32_e32 v7, 0
	v_mov_b32_e32 v8, 0
	v_mov_b32_e32 v9, 0
	v_mov_b32_e32 v10, 0
	v_mov_b32_e32 v11, 0
	v_mov_b32_e32 v12, 0
	v_mov_b32_e32 v13, 0
	v_mov_b32_e32 v14, 0
	v_mov_b32_e32 v15, 0
.Lw_step:
	s_cmp_lg_u32 s10, 0
	s_cbranch_scc1 .Lw_nofirst
	s_lshl_b32 s0, s8, 7
	s_add_u32 s24, s36, s0
	s_addc_u32 s25, s37, 0
	v_lshlrev_b32_e32 v40, 7, v53
	v_add_u32_e32 v40, s56, v40
	global_load_ushort v52, v40, s[24:25]
	s_add_i32 s0, s6, 1
	s_cmp_lt_i32 s0, 8
	s_cselect_b32 s0, 16, 0
	s_add_i32 s0, s8, s0
	s_lshl_b32 s0, s0, 11
	s_add_u32 s62, s34, s0
	s_addc_u32 s63, s35, 0
	v_lshlrev_b32_e32 v40, 11, v53
	v_lshl_add_u32 v40, v55, 1, v40
	v_add_u32_e32 v40, s39, v40
	global_load_dwordx4 v[24:27], v40, s[62:63]
	global_load_dwordx4 v[28:31], v40, s[62:63] offset:64
.Lw_nofirst:
	s_waitcnt vmcnt(6) lgkmcnt(0)
	s_barrier
	s_add_i32 s0, s21, 1
	s_cmp_lt_i32 s0, s29
	s_cbranch_scc1 .Lw_pfsames
	s_cmp_ge_i32 s38, 7
	s_cbranch_scc1 .Lw_pfgos
	s_add_i32 s38, s38, 1
	s_add_i32 s3, s3, 1
	s_lshl_b32 s1, s3, 4
	s_add_i32 s0, s1, 0xfffffe01
	s_max_i32 s0, s0, 0
	s_lshr_b32 s0, s0, 4
	s_and_b32 s11, s0, -2
	s_sub_i32 s0, s3, s11
	s_lshr_b32 s0, s0, 1
	s_add_i32 s29, s0, 1
	s_mov_b32 s21, 0
	s_branch .Lw_pfgos

.Lw_pfgos:
	s_add_i32 s2, s18, 7
	s_and_b32 s2, s2, 7
	s_lshl_b32 s0, s2, 13
	s_add_i32 m0, s0, s23
	s_lshl_b32 s0, s11, 11
	s_add_u32 s16, s12, s0
	s_addc_u32 s17, s13, 0
	global_load_lds_dwordx4 v96, s[16:17]
	s_lshl_b32 s0, s18, 13
	v_add_u32_e32 v40, s0, v97
	ds_read_b128 v[56:59], v40 offset:0
	ds_read_b128 v[60:63], v40 offset:1024
	ds_read_b128 v[68:71], v40 offset:2048
	ds_read_b128 v[72:75], v40 offset:3072
	ds_read_b128 v[76:79], v40 offset:4096
	ds_read_b128 v[80:83], v40 offset:5120
	ds_read_b128 v[84:87], v40 offset:6144
	ds_read_b128 v[92:95], v40 offset:7168
	s_add_i32 s18, s18, 1
	s_and_b32 s18, s18, 7
	s_waitcnt lgkmcnt(4)
	v_mfma_f32_16x16x32_bf16 v[32:35], v[56:59], v[16:19], 0
	v_mfma_f32_16x16x32_bf16 v[36:39], v[68:71], v[16:19], 0
	v_mfma_f32_16x16x32_bf16 v[32:35], v[60:63], v[20:23], v[32:35]
	v_mfma_f32_16x16x32_bf16 v[36:39], v[72:75], v[20:23], v[36:39]
	ds_read_b32 v40, v50 offset:76
	ds_read_b32 v41, v50 offset:72
	ds_read_b32 v42, v50 offset:68
	ds_read_b32 v43, v50 offset:64
	ds_read_b32 v44, v50 offset:12
	ds_read_b32 v45, v50 offset:8
	ds_read_b32 v46, v50 offset:4
	ds_read_b32 v47, v50 offset:0
	v_add_u32_e32 v50, 0xffffff80, v50
	s_waitcnt lgkmcnt(0)
	v_pk_fma_f32 v[32:33], v[32:33], s[40:41], v[40:41] op_sel_hi:[1,0,1]
	v_pk_fma_f32 v[34:35], v[34:35], s[40:41], v[42:43] op_sel_hi:[1,0,1]
	v_pk_fma_f32 v[36:37], v[36:37], s[40:41], v[44:45] op_sel_hi:[1,0,1]
	v_pk_fma_f32 v[38:39], v[38:39], s[40:41], v[46:47] op_sel_hi:[1,0,1]
	v_max3_f32 v40, v32, v33, v34
	v_max3_f32 v41, v35, v36, v37
	v_max3_f32 v40, v40, v38, v39
	v_max_f32_e32 v40, v40, v41
	ds_bpermute_b32 v41, v64, v40
	s_waitcnt lgkmcnt(0)
	v_max_f32_e32 v40, v40, v41
	ds_bpermute_b32 v41, v66, v40
	s_waitcnt lgkmcnt(0)
	v_max_f32_e32 v42, v40, v41
	v_cmp_gt_f32_e32 vcc, v42, v48
	s_cbranch_vccz .Lw_noresc
	v_max_f32_e32 v42, v48, v42
	v_sub_f32_e32 v40, v48, v42
	v_exp_f32_e32 v40, v40
	v_mov_b32_e32 v48, v42
	s_nop 0
	v_pk_mul_f32 v[0:1], v[0:1], v[40:41] op_sel_hi:[1,0]
	v_pk_mul_f32 v[2:3], v[2:3], v[40:41] op_sel_hi:[1,0]
	v_pk_mul_f32 v[4:5], v[4:5], v[40:41] op_sel_hi:[1,0]
	v_pk_mul_f32 v[6:7], v[6:7], v[40:41] op_sel_hi:[1,0]
	v_pk_mul_f32 v[8:9], v[8:9], v[40:41] op_sel_hi:[1,0]
	v_pk_mul_f32 v[10:11], v[10:11], v[40:41] op_sel_hi:[1,0]
	v_pk_mul_f32 v[12:13], v[12:13], v[40:41] op_sel_hi:[1,0]
	v_pk_mul_f32 v[14:15], v[14:15], v[40:41] op_sel_hi:[1,0]
	v_mul_f32_e32 v49, v49, v40
.Lw_noresc:
	v_pk_add_f32 v[32:33], v[32:33], v[48:49] op_sel_hi:[1,0] neg_lo:[0,1] neg_hi:[0,1]
	v_pk_add_f32 v[34:35], v[34:35], v[48:49] op_sel_hi:[1,0] neg_lo:[0,1] neg_hi:[0,1]
	v_pk_add_f32 v[36:37], v[36:37], v[48:49] op_sel_hi:[1,0] neg_lo:[0,1] neg_hi:[0,1]
	v_pk_add_f32 v[38:39], v[38:39], v[48:49] op_sel_hi:[1,0] neg_lo:[0,1] neg_hi:[0,1]
	v_exp_f32_e32 v32, v32
	v_exp_f32_e32 v33, v33
	v_exp_f32_e32 v34, v34
	v_exp_f32_e32 v35, v35
	v_exp_f32_e32 v36, v36
	v_exp_f32_e32 v37, v37
	v_exp_f32_e32 v38, v38
	v_exp_f32_e32 v39, v39
	s_nop 0
	v_pk_add_f32 v[40:41], v[32:33], v[34:35]
	v_pk_add_f32 v[40:41], v[40:41], v[36:37]
	v_pk_add_f32 v[40:41], v[40:41], v[38:39]
	v_add_f32_e32 v40, v40, v41
	v_add_f32_e32 v49, v49, v40
	v_cvt_pk_bf16_f32 v32, v32, v33
	v_cvt_pk_bf16_f32 v33, v34, v35
	v_cvt_pk_bf16_f32 v34, v36, v37
	v_cvt_pk_bf16_f32 v35, v38, v39
	s_nop 1
	v_mfma_f32_16x16x32_bf16 v[0:3], v[76:79], v[32:35], v[0:3]
	v_mfma_f32_16x16x32_bf16 v[4:7], v[80:83], v[32:35], v[4:7]
	v_mfma_f32_16x16x32_bf16 v[8:11], v[84:87], v[32:35], v[8:11]
	v_mfma_f32_16x16x32_bf16 v[12:15], v[92:95], v[32:35], v[12:15]
	s_add_i32 s10, s10, 1
	s_cmp_ge_i32 s10, s9
	s_cbranch_scc0 .Lw_step
	s_cmp_ge_i32 s9, 5
	s_cbranch_scc1 .Lw_ep_go
	s_waitcnt vmcnt(0)
.Lw_ep_go:
	s_nop 7
	ds_bpermute_b32 v40, v64, v49
	s_waitcnt lgkmcnt(0)
	v_add_f32_e32 v49, v49, v40
	ds_bpermute_b32 v40, v66, v49
	v_lshlrev_b32_e32 v42, 16, v52
	v_mul_f32_e32 v42, 0xbfb8aa3b, v42
	v_exp_f32_e32 v42, v42
	s_waitcnt lgkmcnt(0)
	v_add_f32_e32 v49, v49, v40
	v_add_f32_e32 v42, 1.0, v42
	v_mul_f32_e32 v42, v42, v49
	v_rcp_f32_e32 v42, v42
	s_nop 0
	v_pk_mul_f32 v[0:1], v[0:1], v[42:43] op_sel_hi:[1,0]
	v_pk_mul_f32 v[2:3], v[2:3], v[42:43] op_sel_hi:[1,0]
	v_pk_mul_f32 v[4:5], v[4:5], v[42:43] op_sel_hi:[1,0]
	v_pk_mul_f32 v[6:7], v[6:7], v[42:43] op_sel_hi:[1,0]
	v_pk_mul_f32 v[8:9], v[8:9], v[42:43] op_sel_hi:[1,0]
	v_pk_mul_f32 v[10:11], v[10:11], v[42:43] op_sel_hi:[1,0]
	v_pk_mul_f32 v[12:13], v[12:13], v[42:43] op_sel_hi:[1,0]
	v_pk_mul_f32 v[14:15], v[14:15], v[42:43] op_sel_hi:[1,0]
	s_mul_i32 s0, s8, 0x1800
	s_add_i32 s0, s0, 0x1000
	s_add_u32 s24, s30, s0
	s_addc_u32 s25, s31, 0
	v_mul_u32_u24_e32 v44, 0x1800, v53
	v_add_u32_e32 v44, v44, v55
	v_add_u32_e32 v44, s39, v44
	v_cvt_pk_bf16_f32 v0, v0, v1
	v_cvt_pk_bf16_f32 v1, v2, v3
	global_store_dwordx2 v44, v[0:1], s[24:25] offset:0
	v_cvt_pk_bf16_f32 v4, v4, v5
	v_cvt_pk_bf16_f32 v5, v6, v7
	global_store_dwordx2 v44, v[4:5], s[24:25] offset:32
	v_cvt_pk_bf16_f32 v8, v8, v9
	v_cvt_pk_bf16_f32 v9, v10, v11
	global_store_dwordx2 v44, v[8:9], s[24:25] offset:64
	v_cvt_pk_bf16_f32 v12, v12, v13
	v_cvt_pk_bf16_f32 v13, v14, v15
	global_store_dwordx2 v44, v[12:13], s[24:25] offset:96
	s_add_i32 s6, s6, 1
	s_cmp_ge_i32 s6, 8
	s_cbranch_scc1 .Lw_exit
	s_add_i32 s7, s7, 1
	s_lshl_b32 s8, s7, 4
	s_add_i32 s0, s8, 0xfffffe01
	s_max_i32 s0, s0, 0
	s_lshr_b32 s0, s0, 4
	s_and_b32 s1, s0, -2
	s_sub_i32 s0, s7, s1
	s_lshr_b32 s0, s0, 1
	s_add_i32 s9, s0, 1
	s_mov_b32 s10, 0
	s_lshl_b32 s0, s1, 4
	s_sub_i32 s0, s8, s0
	s_add_i32 s0, s0, 13
	s_lshl_b32 s0, s0, 2
	s_add_i32 s0, s0, s28
	v_sub_u32_e32 v50, v53, v54
	v_lshl_add_u32 v50, v50, 2, s0
	v_mov_b32_e32 v16, v24
	v_mov_b32_e32 v20, v28
	v_mov_b32_e32 v17, v25
	v_mov_b32_e32 v21, v29
	v_mov_b32_e32 v18, v26
	v_mov_b32_e32 v22, v30
	v_mov_b32_e32 v19, v27
	v_mov_b32_e32 v23, v31
	v_mov_b32_e32 v48, 0xefa18f08
	v_mov_b32_e32 v49, 0
	s_nop 0
	v_mov_b32_e32 v0, 0
	v_mov_b32_e32 v1, 0
	v_mov_b32_e32 v2, 0
	v_mov_b32_e32 v3, 0
	v_mov_b32_e32 v4, 0
	v_mov_b32_e32 v5, 0
	v_mov_b32_e32 v6, 0
	v_mov_b32_e32 v7, 0
	v_mov_b32_e32 v8, 0
	v_mov_b32_e32 v9, 0
	v_mov_b32_e32 v10, 0
	v_mov_b32_e32 v11, 0
	v_mov_b32_e32 v12, 0
	v_mov_b32_e32 v13, 0
	v_mov_b32_e32 v14, 0
	v_mov_b32_e32 v15, 0
	s_branch .Lw_step
.Lw_exit:
	s_waitcnt vmcnt(0)
	s_branch .LBB0_493
.Lwin_generic:
	s_movk_i32 s0, 0x4000
	v_cmp_gt_i32_e32 vcc, s0, v89
	s_and_saveexec_b64 s[38:39], vcc
	s_cbranch_execz .LBB0_445
	v_sub_u32_e32 v0, v102, v88
	v_lshl_or_b32 v64, v102, 6, v86
	v_subrev_u32_e32 v87, 19, v0
	v_lshl_add_u64 v[0:1], s[26:27], 0, v[64:65]
	s_mov_b64 s[0:1], 0x1e100000
	v_lshlrev_b32_e32 v85, 4, v89
	v_lshl_add_u64 v[90:91], v[0:1], 0, s[0:1]
	s_mov_b64 s[40:41], 0
	v_lshlrev_b32_e32 v92, 1, v88
	s_branch .LBB0_404

.LBB0_841:
	s_andn2_b64 vcc, exec, s[0:1]
	v_readlane_b32 s3, v254, 47
	s_cbranch_vccnz .LBB0_934
	s_mov_b64 s[22:23], exec
	s_and_b32 s2, s3, 1
	s_lshr_b32 s0, s3, 1
	s_and_b32 s0, s0, 3
	s_lshl_b32 s26, s0, 12
	s_add_i32 s27, s26, 0x1000
	v_readfirstlane_b32 s1, v220
	s_and_b32 s0, s3, -8
	s_add_i32 s0, s0, s1
	s_add_i32 s26, s26, s0
	s_lshl_b32 s0, s2, 6
	s_add_u32 s12, s12, s0
	s_addc_u32 s13, s13, 0
	s_lshl_b32 s0, s2, 21
	s_add_u32 s18, s18, s0
	s_addc_u32 s19, s19, 0
	s_add_u32 s16, s16, s0
	s_addc_u32 s17, s17, 0
	v_lshl_or_b32 v202, s2, 3, v200
	v_and_b32_e32 v140, 63, v208
	v_lshlrev_b32_e32 v140, 4, v140
	v_add_u32_e32 v141, 0x1000, v140
	s_mov_b32 s48, 0x3e38aa3b
	s_mov_b32 s49, 0x3e38aa3b
	s_mov_b32 s57, 0x20400
	v_mov_b32_e32 v179, 0xf149f2ca
	v_lshl_add_u32 v66, v202, 2, s57
	ds_read_b32 v178, v66 offset:1984
	s_lshl_b32 s0, s26, 7
	s_add_u32 s38, s12, s0
	s_addc_u32 s39, s13, 0
	v_lshrrev_b32_e32 v144, 3, v199
	global_load_dword v176, v144, s[38:39]
	s_lshl_b32 s0, s26, 11
	s_add_u32 s54, s14, s0
	s_addc_u32 s55, s15, 0
	v_lshlrev_b32_e32 v67, 7, v202
	v_lshl_add_u32 v67, v198, 1, v67
	global_load_dwordx4 v[16:19], v67, s[54:55]
	global_load_dwordx4 v[20:23], v67, s[54:55] offset:64
	s_mov_b64 s[34:35], s[18:19]
	s_mov_b64 s[36:37], s[16:17]
	global_load_dwordx4 v[32:35], v140, s[34:35] offset:0
	global_load_dwordx4 v[36:39], v140, s[34:35] offset:1024
	global_load_dwordx4 v[40:43], v140, s[34:35] offset:2048
	global_load_dwordx4 v[44:47], v140, s[34:35] offset:3072
	global_load_dwordx4 v[48:51], v141, s[34:35] offset:0
	global_load_dwordx4 v[52:55], v141, s[34:35] offset:1024
	global_load_dwordx4 v[56:59], v141, s[34:35] offset:2048
	global_load_dwordx4 v[60:63], v141, s[34:35] offset:3072
	global_load_dwordx4 v[100:103], v140, s[36:37] offset:0
	global_load_dwordx4 v[104:107], v140, s[36:37] offset:1024
	global_load_dwordx4 v[108:111], v140, s[36:37] offset:2048
	global_load_dwordx4 v[112:115], v140, s[36:37] offset:3072
	global_load_dwordx4 v[116:119], v141, s[36:37] offset:0
	global_load_dwordx4 v[120:123], v141, s[36:37] offset:1024
	global_load_dwordx4 v[124:127], v141, s[36:37] offset:2048
	global_load_dwordx4 v[128:131], v141, s[36:37] offset:3072
	s_lshr_b32 s0, s26, 6
	s_add_i32 s0, s0, 1
	s_min_i32 s28, s0, 16
	s_mov_b32 s29, 0
	s_mov_b32 s30, 0
	s_mov_b32 s51, 0
	v_mov_b32_e32 v196, 0xf149f2ca
	v_mov_b32_e32 v197, 0
	v_mov_b32_e32 v0, 0
	v_mov_b32_e32 v1, 0
	v_mov_b32_e32 v2, 0
	v_mov_b32_e32 v3, 0
	v_mov_b32_e32 v4, 0
	v_mov_b32_e32 v5, 0
	v_mov_b32_e32 v6, 0
	v_mov_b32_e32 v7, 0
	v_mov_b32_e32 v8, 0
	v_mov_b32_e32 v9, 0
	v_mov_b32_e32 v10, 0
	v_mov_b32_e32 v11, 0
	v_mov_b32_e32 v12, 0
	v_mov_b32_e32 v13, 0
	v_mov_b32_e32 v14, 0
	v_mov_b32_e32 v15, 0
	s_waitcnt lgkmcnt(0)
	v_mul_f32_e32 v178, 0x3fb8aa3b, v178
	s_waitcnt vmcnt(18)
